# SwiGLU epilogues hand-rewritten: 7 VALU per output ((g*u)*rs^2 * rcp(1+exp2(g*c))), running store address, no register shuffles
# speedup vs baseline: 1.0130x; 1.0066x over previous
.LBB0_227:
	s_add_u32 s54, s46, 0xfffc0080
	s_addc_u32 s55, s47, -1
	s_add_i32 s76, 16, 0x10000
	s_cmp_eq_u32 s78, 12
	s_cselect_b32 s61, s15, s55
	s_cselect_b32 s60, s72, s54
	v_add_u32_e32 v80, s76, v146
	s_cselect_b32 s55, s11, s75
	s_cselect_b32 s54, s73, s74
	s_add_i32 s77, 16, 0x14000
	ds_read_b128 v[142:145], v80
	ds_read_b128 v[148:151], v80 offset:1024
	ds_read_b128 v[160:163], v80 offset:2048
	ds_read_b128 v[164:167], v80 offset:3072
	v_add_u32_e32 v80, s77, v146
	ds_read_b128 v[168:171], v80
	ds_read_b128 v[172:175], v80 offset:1024
	ds_read_b128 v[176:179], v80 offset:2048
	ds_read_b128 v[180:183], v80 offset:3072
	v_lshl_add_u64 v[208:209], s[46:47], 0, v[138:139]
	s_add_i32 m0, s13, 0xc000
	ds_read_b128 v[184:187], v147
	ds_read_b128 v[188:191], v147 offset:1024
	ds_read_b128 v[204:207], v147 offset:2048
	ds_read_b128 v[214:217], v147 offset:3072
	ds_read_b128 v[218:221], v147 offset:4096
	ds_read_b128 v[222:225], v147 offset:5120
	ds_read_b128 v[226:229], v147 offset:6144
	ds_read_b128 v[230:233], v147 offset:7168
	global_load_lds_dwordx4 v[208:209], off
	v_lshl_add_u64 v[208:209], s[46:47], 0, v[140:141]
	s_add_i32 m0, s13, 0xe000
	s_nop 0
	global_load_lds_dwordx4 v[208:209], off
	s_waitcnt vmcnt(8)
	s_waitcnt lgkmcnt(0)
	s_barrier
	s_waitcnt lgkmcnt(0)
	v_mfma_f32_16x16x32_bf16 v[118:121], v[142:145], v[184:187], v[118:121]
	v_mfma_f32_16x16x32_bf16 v[114:117], v[160:163], v[184:187], v[114:117]
	v_mfma_f32_16x16x32_bf16 v[106:109], v[142:145], v[204:207], v[106:109]
	v_mfma_f32_16x16x32_bf16 v[98:101], v[160:163], v[204:207], v[98:101]
	v_mfma_f32_16x16x32_bf16 v[90:93], v[142:145], v[218:221], v[90:93]
	v_mfma_f32_16x16x32_bf16 v[82:85], v[160:163], v[218:221], v[82:85]
	v_mfma_f32_16x16x32_bf16 v[68:71], v[142:145], v[226:229], v[68:71]
	v_mfma_f32_16x16x32_bf16 v[64:67], v[160:163], v[226:229], v[64:67]
	v_mfma_f32_16x16x32_bf16 v[118:121], v[148:151], v[188:191], v[118:121]
	v_mfma_f32_16x16x32_bf16 v[114:117], v[164:167], v[188:191], v[114:117]
	v_mfma_f32_16x16x32_bf16 v[106:109], v[148:151], v[214:217], v[106:109]
	v_mfma_f32_16x16x32_bf16 v[98:101], v[164:167], v[214:217], v[98:101]
	v_mfma_f32_16x16x32_bf16 v[90:93], v[148:151], v[222:225], v[90:93]
	v_mfma_f32_16x16x32_bf16 v[82:85], v[164:167], v[222:225], v[82:85]
	v_mfma_f32_16x16x32_bf16 v[68:71], v[148:151], v[230:233], v[68:71]
	v_mfma_f32_16x16x32_bf16 v[64:67], v[164:167], v[230:233], v[64:67]
	v_mfma_f32_16x16x32_bf16 v[126:129], v[168:171], v[184:187], v[126:129]
	v_mfma_f32_16x16x32_bf16 v[122:125], v[176:179], v[184:187], v[122:125]
	v_mfma_f32_16x16x32_bf16 v[110:113], v[168:171], v[204:207], v[110:113]
	v_mfma_f32_16x16x32_bf16 v[102:105], v[176:179], v[204:207], v[102:105]
	v_mfma_f32_16x16x32_bf16 v[94:97], v[168:171], v[218:221], v[94:97]
	v_mfma_f32_16x16x32_bf16 v[86:89], v[176:179], v[218:221], v[86:89]
	v_mfma_f32_16x16x32_bf16 v[76:79], v[168:171], v[226:229], v[76:79]
	v_mfma_f32_16x16x32_bf16 v[72:75], v[176:179], v[226:229], v[72:75]
	v_mfma_f32_16x16x32_bf16 v[126:129], v[172:175], v[188:191], v[126:129]
	v_mfma_f32_16x16x32_bf16 v[122:125], v[180:183], v[188:191], v[122:125]
	v_mfma_f32_16x16x32_bf16 v[110:113], v[172:175], v[214:217], v[110:113]
	v_mfma_f32_16x16x32_bf16 v[102:105], v[180:183], v[214:217], v[102:105]
	v_mfma_f32_16x16x32_bf16 v[94:97], v[172:175], v[222:225], v[94:97]
	v_mfma_f32_16x16x32_bf16 v[86:89], v[180:183], v[222:225], v[86:89]
	v_mfma_f32_16x16x32_bf16 v[76:79], v[172:175], v[230:233], v[76:79]
	v_mfma_f32_16x16x32_bf16 v[72:75], v[180:183], v[230:233], v[72:75]
	s_barrier
	s_add_i32 s76, s76, s4
	v_lshl_add_u64 v[208:209], s[54:55], 0, v[134:135]
	s_mov_b32 m0, s76
	ds_read_b128 v[184:187], v147 offset:16384
	ds_read_b128 v[188:191], v147 offset:17408
	ds_read_b128 v[204:207], v147 offset:18432
	ds_read_b128 v[214:217], v147 offset:19456
	ds_read_b128 v[218:221], v147 offset:20480
	ds_read_b128 v[222:225], v147 offset:21504
	ds_read_b128 v[226:229], v147 offset:22528
	ds_read_b128 v[230:233], v147 offset:23552
	global_load_lds_dwordx4 v[208:209], off
	s_add_i32 m0, s76, 0x2000
	s_add_u32 s96, s54, 0x40000
	v_lshl_add_u64 v[234:235], s[54:55], 0, v[130:131]
	s_addc_u32 s97, s55, 0
	s_add_i32 s76, s77, s4
	global_load_lds_dwordx4 v[234:235], off
	v_lshl_add_u64 v[236:237], s[96:97], 0, v[134:135]
	s_mov_b32 m0, s76
	v_lshl_add_u64 v[238:239], s[60:61], 0, v[132:133]
	global_load_lds_dwordx4 v[236:237], off
	v_lshl_add_u64 v[236:237], s[96:97], 0, v[130:131]
	s_add_i32 m0, s76, 0x2000
	s_nop 0
	global_load_lds_dwordx4 v[236:237], off
	v_lshl_add_u64 v[236:237], s[60:61], 0, v[136:137]
	s_mov_b32 m0, s13
	s_nop 0
	global_load_lds_dwordx4 v[236:237], off
	s_mov_b32 m0, s25
	s_nop 0
	global_load_lds_dwordx4 v[238:239], off
	s_waitcnt vmcnt(8)
	s_waitcnt lgkmcnt(0)
	s_barrier
	s_waitcnt lgkmcnt(0)
	v_mfma_f32_16x16x32_bf16 v[52:55], v[142:145], v[184:187], v[52:55]
	v_mfma_f32_16x16x32_bf16 v[48:51], v[160:163], v[184:187], v[48:51]
	v_mfma_f32_16x16x32_bf16 v[36:39], v[142:145], v[204:207], v[36:39]
	v_mfma_f32_16x16x32_bf16 v[32:35], v[160:163], v[204:207], v[32:35]
	v_mfma_f32_16x16x32_bf16 v[20:23], v[142:145], v[218:221], v[20:23]
	v_mfma_f32_16x16x32_bf16 v[16:19], v[160:163], v[218:221], v[16:19]
	v_mfma_f32_16x16x32_bf16 v[8:11], v[142:145], v[226:229], v[8:11]
	v_mfma_f32_16x16x32_bf16 v[0:3], v[160:163], v[226:229], v[0:3]
	v_mfma_f32_16x16x32_bf16 v[52:55], v[148:151], v[188:191], v[52:55]
	v_mfma_f32_16x16x32_bf16 v[48:51], v[164:167], v[188:191], v[48:51]
	v_mfma_f32_16x16x32_bf16 v[36:39], v[148:151], v[214:217], v[36:39]
	v_mfma_f32_16x16x32_bf16 v[32:35], v[164:167], v[214:217], v[32:35]
	v_mfma_f32_16x16x32_bf16 v[20:23], v[148:151], v[222:225], v[20:23]
	v_mfma_f32_16x16x32_bf16 v[16:19], v[164:167], v[222:225], v[16:19]
	v_mfma_f32_16x16x32_bf16 v[8:11], v[148:151], v[230:233], v[8:11]
	v_mfma_f32_16x16x32_bf16 v[0:3], v[164:167], v[230:233], v[0:3]
	v_mfma_f32_16x16x32_bf16 v[60:63], v[168:171], v[184:187], v[60:63]
	v_mfma_f32_16x16x32_bf16 v[56:59], v[176:179], v[184:187], v[56:59]
	v_mfma_f32_16x16x32_bf16 v[44:47], v[168:171], v[204:207], v[44:47]
	v_mfma_f32_16x16x32_bf16 v[40:43], v[176:179], v[204:207], v[40:43]
	v_mfma_f32_16x16x32_bf16 v[28:31], v[168:171], v[218:221], v[28:31]
	v_mfma_f32_16x16x32_bf16 v[24:27], v[176:179], v[218:221], v[24:27]
	v_mfma_f32_16x16x32_bf16 v[12:15], v[168:171], v[226:229], v[12:15]
	v_mfma_f32_16x16x32_bf16 v[4:7], v[176:179], v[226:229], v[4:7]
	v_mfma_f32_16x16x32_bf16 v[60:63], v[172:175], v[188:191], v[60:63]
	v_mfma_f32_16x16x32_bf16 v[56:59], v[180:183], v[188:191], v[56:59]
	v_mfma_f32_16x16x32_bf16 v[44:47], v[172:175], v[214:217], v[44:47]
	v_mfma_f32_16x16x32_bf16 v[40:43], v[180:183], v[214:217], v[40:43]
	v_mfma_f32_16x16x32_bf16 v[28:31], v[172:175], v[222:225], v[28:31]
	v_mfma_f32_16x16x32_bf16 v[24:27], v[180:183], v[222:225], v[24:27]
	v_mfma_f32_16x16x32_bf16 v[12:15], v[172:175], v[230:233], v[12:15]
	v_mfma_f32_16x16x32_bf16 v[4:7], v[180:183], v[230:233], v[4:7]
	s_barrier
	s_add_i32 s76, 16, 0x18000
	v_add_u32_e32 v80, s76, v146
	s_add_i32 s77, 16, 0x1c000
	ds_read_b128 v[142:145], v80
	ds_read_b128 v[148:151], v80 offset:1024
	ds_read_b128 v[160:163], v80 offset:2048
	ds_read_b128 v[164:167], v80 offset:3072
	v_add_u32_e32 v80, s77, v146
	ds_read_b128 v[168:171], v80
	ds_read_b128 v[172:175], v80 offset:1024
	ds_read_b128 v[176:179], v80 offset:2048
	ds_read_b128 v[180:183], v80 offset:3072
	s_add_u32 s60, s60, 0x40000
	s_addc_u32 s61, s61, 0
	s_mov_b32 m0, s30
	v_lshl_add_u64 v[240:241], s[60:61], 0, v[136:137]
	ds_read_b128 v[184:187], v147 offset:32768
	ds_read_b128 v[188:191], v147 offset:33792
	ds_read_b128 v[204:207], v147 offset:34816
	ds_read_b128 v[214:217], v147 offset:35840
	ds_read_b128 v[218:221], v147 offset:36864
	ds_read_b128 v[222:225], v147 offset:37888
	ds_read_b128 v[226:229], v147 offset:38912
	ds_read_b128 v[230:233], v147 offset:39936
	global_load_lds_dwordx4 v[240:241], off
	v_lshl_add_u64 v[240:241], s[60:61], 0, v[132:133]
	s_mov_b32 m0, s33
	s_nop 0
	global_load_lds_dwordx4 v[240:241], off
	s_waitcnt vmcnt(8)
	s_waitcnt lgkmcnt(0)
	s_barrier
	s_waitcnt lgkmcnt(0)
	v_mfma_f32_16x16x32_bf16 v[118:121], v[142:145], v[184:187], v[118:121]
	v_mfma_f32_16x16x32_bf16 v[114:117], v[160:163], v[184:187], v[114:117]
	v_mfma_f32_16x16x32_bf16 v[106:109], v[142:145], v[204:207], v[106:109]
	v_mfma_f32_16x16x32_bf16 v[98:101], v[160:163], v[204:207], v[98:101]
	v_mfma_f32_16x16x32_bf16 v[90:93], v[142:145], v[218:221], v[90:93]
	v_mfma_f32_16x16x32_bf16 v[82:85], v[160:163], v[218:221], v[82:85]
	v_mfma_f32_16x16x32_bf16 v[68:71], v[142:145], v[226:229], v[68:71]
	v_mfma_f32_16x16x32_bf16 v[64:67], v[160:163], v[226:229], v[64:67]
	v_mfma_f32_16x16x32_bf16 v[118:121], v[148:151], v[188:191], v[118:121]
	v_mfma_f32_16x16x32_bf16 v[114:117], v[164:167], v[188:191], v[114:117]
	v_mfma_f32_16x16x32_bf16 v[106:109], v[148:151], v[214:217], v[106:109]
	v_mfma_f32_16x16x32_bf16 v[98:101], v[164:167], v[214:217], v[98:101]
	v_mfma_f32_16x16x32_bf16 v[90:93], v[148:151], v[222:225], v[90:93]
	v_mfma_f32_16x16x32_bf16 v[82:85], v[164:167], v[222:225], v[82:85]
	v_mfma_f32_16x16x32_bf16 v[68:71], v[148:151], v[230:233], v[68:71]
	v_mfma_f32_16x16x32_bf16 v[64:67], v[164:167], v[230:233], v[64:67]
	v_mfma_f32_16x16x32_bf16 v[126:129], v[168:171], v[184:187], v[126:129]
	v_mfma_f32_16x16x32_bf16 v[122:125], v[176:179], v[184:187], v[122:125]
	v_mfma_f32_16x16x32_bf16 v[110:113], v[168:171], v[204:207], v[110:113]
	v_mfma_f32_16x16x32_bf16 v[102:105], v[176:179], v[204:207], v[102:105]
	v_mfma_f32_16x16x32_bf16 v[94:97], v[168:171], v[218:221], v[94:97]
	v_mfma_f32_16x16x32_bf16 v[86:89], v[176:179], v[218:221], v[86:89]
	v_mfma_f32_16x16x32_bf16 v[76:79], v[168:171], v[226:229], v[76:79]
	v_mfma_f32_16x16x32_bf16 v[72:75], v[176:179], v[226:229], v[72:75]
	v_mfma_f32_16x16x32_bf16 v[126:129], v[172:175], v[188:191], v[126:129]
	v_mfma_f32_16x16x32_bf16 v[122:125], v[180:183], v[188:191], v[122:125]
	v_mfma_f32_16x16x32_bf16 v[110:113], v[172:175], v[214:217], v[110:113]
	v_mfma_f32_16x16x32_bf16 v[102:105], v[180:183], v[214:217], v[102:105]
	v_mfma_f32_16x16x32_bf16 v[94:97], v[172:175], v[222:225], v[94:97]
	v_mfma_f32_16x16x32_bf16 v[86:89], v[180:183], v[222:225], v[86:89]
	v_mfma_f32_16x16x32_bf16 v[76:79], v[172:175], v[230:233], v[76:79]
	v_mfma_f32_16x16x32_bf16 v[72:75], v[180:183], v[230:233], v[72:75]
	s_barrier
	s_add_i32 s60, s76, s4
	v_lshl_add_u64 v[208:209], v[208:209], 0, s[20:21]
	s_mov_b32 m0, s60
	ds_read_b128 v[184:187], v147 offset:49152
	ds_read_b128 v[188:191], v147 offset:50176
	ds_read_b128 v[204:207], v147 offset:51200
	ds_read_b128 v[214:217], v147 offset:52224
	ds_read_b128 v[218:221], v147 offset:53248
	ds_read_b128 v[222:225], v147 offset:54272
	ds_read_b128 v[226:229], v147 offset:55296
	ds_read_b128 v[230:233], v147 offset:56320
	global_load_lds_dwordx4 v[208:209], off
	s_add_i32 m0, s60, 0x2000
	s_add_u32 s54, s54, 0x40080
	v_lshl_add_u64 v[208:209], v[234:235], 0, s[20:21]
	s_addc_u32 s55, s55, 0
	s_add_i32 s60, s77, s4
	global_load_lds_dwordx4 v[208:209], off
	v_lshl_add_u64 v[208:209], s[54:55], 0, v[134:135]
	s_mov_b32 m0, s60
	s_nop 0
	global_load_lds_dwordx4 v[208:209], off
	v_lshl_add_u64 v[208:209], s[54:55], 0, v[130:131]
	s_add_i32 m0, s60, 0x2000
	s_nop 0
	global_load_lds_dwordx4 v[208:209], off
	v_lshl_add_u64 v[208:209], v[236:237], 0, s[20:21]
	s_mov_b32 m0, s34
	s_nop 0
	global_load_lds_dwordx4 v[208:209], off
	v_lshl_add_u64 v[208:209], v[238:239], 0, s[20:21]
	s_mov_b32 m0, s36
	s_nop 0
	global_load_lds_dwordx4 v[208:209], off
	s_waitcnt vmcnt(8)
	s_waitcnt lgkmcnt(0)
	s_barrier
	s_waitcnt lgkmcnt(0)
	v_mfma_f32_16x16x32_bf16 v[52:55], v[142:145], v[184:187], v[52:55]
	v_mfma_f32_16x16x32_bf16 v[48:51], v[160:163], v[184:187], v[48:51]
	v_mfma_f32_16x16x32_bf16 v[36:39], v[142:145], v[204:207], v[36:39]
	v_mfma_f32_16x16x32_bf16 v[32:35], v[160:163], v[204:207], v[32:35]
	v_mfma_f32_16x16x32_bf16 v[20:23], v[142:145], v[218:221], v[20:23]
	v_mfma_f32_16x16x32_bf16 v[16:19], v[160:163], v[218:221], v[16:19]
	v_mfma_f32_16x16x32_bf16 v[8:11], v[142:145], v[226:229], v[8:11]
	v_mfma_f32_16x16x32_bf16 v[0:3], v[160:163], v[226:229], v[0:3]
	v_mfma_f32_16x16x32_bf16 v[52:55], v[148:151], v[188:191], v[52:55]
	v_mfma_f32_16x16x32_bf16 v[48:51], v[164:167], v[188:191], v[48:51]
	v_mfma_f32_16x16x32_bf16 v[36:39], v[148:151], v[214:217], v[36:39]
	v_mfma_f32_16x16x32_bf16 v[32:35], v[164:167], v[214:217], v[32:35]
	v_mfma_f32_16x16x32_bf16 v[20:23], v[148:151], v[222:225], v[20:23]
	v_mfma_f32_16x16x32_bf16 v[16:19], v[164:167], v[222:225], v[16:19]
	v_mfma_f32_16x16x32_bf16 v[8:11], v[148:151], v[230:233], v[8:11]
	v_mfma_f32_16x16x32_bf16 v[0:3], v[164:167], v[230:233], v[0:3]
	v_mfma_f32_16x16x32_bf16 v[60:63], v[168:171], v[184:187], v[60:63]
	v_mfma_f32_16x16x32_bf16 v[56:59], v[176:179], v[184:187], v[56:59]
	v_mfma_f32_16x16x32_bf16 v[44:47], v[168:171], v[204:207], v[44:47]
	v_mfma_f32_16x16x32_bf16 v[40:43], v[176:179], v[204:207], v[40:43]
	v_mfma_f32_16x16x32_bf16 v[28:31], v[168:171], v[218:221], v[28:31]
	v_mfma_f32_16x16x32_bf16 v[24:27], v[176:179], v[218:221], v[24:27]
	v_mfma_f32_16x16x32_bf16 v[12:15], v[168:171], v[226:229], v[12:15]
	v_mfma_f32_16x16x32_bf16 v[4:7], v[176:179], v[226:229], v[4:7]
	v_mfma_f32_16x16x32_bf16 v[60:63], v[172:175], v[188:191], v[60:63]
	v_mfma_f32_16x16x32_bf16 v[56:59], v[180:183], v[188:191], v[56:59]
	v_mfma_f32_16x16x32_bf16 v[44:47], v[172:175], v[214:217], v[44:47]
	v_mfma_f32_16x16x32_bf16 v[40:43], v[180:183], v[214:217], v[40:43]
	v_mfma_f32_16x16x32_bf16 v[28:31], v[172:175], v[222:225], v[28:31]
	v_mfma_f32_16x16x32_bf16 v[24:27], v[180:183], v[222:225], v[24:27]
	v_mfma_f32_16x16x32_bf16 v[12:15], v[172:175], v[230:233], v[12:15]
	v_mfma_f32_16x16x32_bf16 v[4:7], v[180:183], v[230:233], v[4:7]
	s_barrier
	s_add_i32 s78, s78, 2
	s_add_u32 s46, s46, 0x100
	s_addc_u32 s47, s47, 0
	s_add_u32 s74, s74, 0x100
	s_addc_u32 s75, s75, 0
	s_cmp_gt_u32 s78, 13
	s_cbranch_scc0 .LBB0_227
	v_ashrrev_i32_e32 v160, 2, v192
	v_and_b32_e32 v160, 0xffffffc0, v160
	s_lshl_b32 s11, s67, 8
	v_and_or_b32 v142, v192, 15, s11
	v_add_u32_e32 v142, v142, v160
	v_ashrrev_i32_e32 v143, 31, v142
	v_lshl_add_u64 v[144:145], v[142:143], 2, s[90:91]
	v_add_co_u32_e32 v144, vcc, 0x40000, v144
	s_nop 1
	v_addc_co_u32_e32 v145, vcc, 0, v145, vcc
	global_load_dword v242, v[144:145], off
	global_load_dword v243, v[144:145], off offset:64
	global_load_dword v244, v[144:145], off offset:128
	global_load_dword v245, v[144:145], off offset:192
	global_load_dword v246, v[144:145], off offset:512
	global_load_dword v247, v[144:145], off offset:576
	global_load_dword v248, v[144:145], off offset:640
	global_load_dword v249, v[144:145], off offset:704
	v_readlane_b32 s54, v254, 40
	s_lshl_b32 s46, s66, 7
	v_readlane_b32 s55, v254, 41
	s_ashr_i32 s47, s46, 31
	s_lshl_b64 s[46:47], s[46:47], 1
	s_nop 0
	v_mov_b64_e32 v[162:163], s[54:55]
	v_mad_i64_i32 v[160:161], s[54:55], v142, s28, v[162:163]
	v_lshl_add_u64 v[160:161], v[160:161], 0, s[46:47]
	v_and_b32_e32 v164, 0xc0, v192
	v_mov_b32_e32 v165, v81
	v_lshl_add_u64 v[160:161], v[160:161], 0, v[164:165]
	v_and_b32_e32 v164, 48, v192
	v_lshl_add_u64 v[160:161], v[160:161], 0, v[164:165]
	s_and_b64 vcc, exec, s[6:7]
	s_cbranch_vccz .Lsw9_go
	s_barrier
.Lsw9_go:
	s_waitcnt vmcnt(7)
	v_fmamk_f32 v166, v242, 0x3a800000, v194
	v_mul_f32_e32 v167, 0x4b800000, v166
	v_cmp_gt_f32_e32 vcc, s19, v166
	s_nop 1
	v_cndmask_b32_e32 v166, v166, v167, vcc
	v_rsq_f32_e32 v166, v166
	s_nop 0
	v_mul_f32_e32 v167, 0x45800000, v166
	v_cndmask_b32_e32 v166, v166, v167, vcc
	v_mul_f32_e32 v167, 0xbfb8aa3b, v166
	v_mul_f32_e32 v168, v166, v166
	v_mul_f32_e32 v169, v118, v167
	v_mul_f32_e32 v170, v119, v167
	v_mul_f32_e32 v171, v120, v167
	v_mul_f32_e32 v172, v121, v167
	v_mul_f32_e32 v173, v114, v167
	v_mul_f32_e32 v174, v115, v167
	v_mul_f32_e32 v175, v116, v167
	v_mul_f32_e32 v176, v117, v167
	v_exp_f32_e32 v169, v169
	v_exp_f32_e32 v170, v170
	v_exp_f32_e32 v171, v171
	v_exp_f32_e32 v172, v172
	v_exp_f32_e32 v173, v173
	v_exp_f32_e32 v174, v174
	v_exp_f32_e32 v175, v175
	v_exp_f32_e32 v176, v176
	v_mul_f32_e32 v118, v118, v126
	v_mul_f32_e32 v119, v119, v127
	v_mul_f32_e32 v120, v120, v128
	v_mul_f32_e32 v121, v121, v129
	v_mul_f32_e32 v114, v114, v122
	v_mul_f32_e32 v115, v115, v123
	v_mul_f32_e32 v116, v116, v124
	v_mul_f32_e32 v117, v117, v125
	v_add_f32_e32 v169, 1.0, v169
	v_add_f32_e32 v170, 1.0, v170
	v_add_f32_e32 v171, 1.0, v171
	v_add_f32_e32 v172, 1.0, v172
	v_add_f32_e32 v173, 1.0, v173
	v_add_f32_e32 v174, 1.0, v174
	v_add_f32_e32 v175, 1.0, v175
	v_add_f32_e32 v176, 1.0, v176
	v_rcp_f32_e32 v169, v169
	v_rcp_f32_e32 v170, v170
	v_rcp_f32_e32 v171, v171
	v_rcp_f32_e32 v172, v172
	v_rcp_f32_e32 v173, v173
	v_rcp_f32_e32 v174, v174
	v_rcp_f32_e32 v175, v175
	v_rcp_f32_e32 v176, v176
	v_mul_f32_e32 v118, v118, v168
	v_mul_f32_e32 v119, v119, v168
	v_mul_f32_e32 v120, v120, v168
	v_mul_f32_e32 v121, v121, v168
	v_mul_f32_e32 v114, v114, v168
	v_mul_f32_e32 v115, v115, v168
	v_mul_f32_e32 v116, v116, v168
	v_mul_f32_e32 v117, v117, v168
	v_mul_f32_e32 v118, v118, v169
	v_mul_f32_e32 v119, v119, v170
	v_mul_f32_e32 v120, v120, v171
	v_mul_f32_e32 v121, v121, v172
	v_mul_f32_e32 v114, v114, v173
	v_mul_f32_e32 v115, v115, v174
	v_mul_f32_e32 v116, v116, v175
	v_mul_f32_e32 v117, v117, v176
	v_cvt_pk_bf16_f32 v184, v118, v119
	v_cvt_pk_bf16_f32 v185, v120, v121
	v_cvt_pk_bf16_f32 v186, v114, v115
	v_cvt_pk_bf16_f32 v187, v116, v117
	global_store_dwordx4 v[160:161], v[184:187], off nt
	v_add_co_u32_e32 v160, vcc, 0x16000, v160
	s_nop 1
	v_addc_co_u32_e32 v161, vcc, 0, v161, vcc
	s_waitcnt vmcnt(7)
	v_fmamk_f32 v166, v243, 0x3a800000, v194
	v_mul_f32_e32 v167, 0x4b800000, v166
	v_cmp_gt_f32_e32 vcc, s19, v166
	s_nop 1
	v_cndmask_b32_e32 v166, v166, v167, vcc
	v_rsq_f32_e32 v166, v166
	s_nop 0
	v_mul_f32_e32 v167, 0x45800000, v166
	v_cndmask_b32_e32 v166, v166, v167, vcc
	v_mul_f32_e32 v167, 0xbfb8aa3b, v166
	v_mul_f32_e32 v168, v166, v166
	v_mul_f32_e32 v169, v106, v167
	v_mul_f32_e32 v170, v107, v167
	v_mul_f32_e32 v171, v108, v167
	v_mul_f32_e32 v172, v109, v167
	v_mul_f32_e32 v173, v98, v167
	v_mul_f32_e32 v174, v99, v167
	v_mul_f32_e32 v175, v100, v167
	v_mul_f32_e32 v176, v101, v167
	v_exp_f32_e32 v169, v169
	v_exp_f32_e32 v170, v170
	v_exp_f32_e32 v171, v171
	v_exp_f32_e32 v172, v172
	v_exp_f32_e32 v173, v173
	v_exp_f32_e32 v174, v174
	v_exp_f32_e32 v175, v175
	v_exp_f32_e32 v176, v176
	v_mul_f32_e32 v106, v106, v110
	v_mul_f32_e32 v107, v107, v111
	v_mul_f32_e32 v108, v108, v112
	v_mul_f32_e32 v109, v109, v113
	v_mul_f32_e32 v98, v98, v102
	v_mul_f32_e32 v99, v99, v103
	v_mul_f32_e32 v100, v100, v104
	v_mul_f32_e32 v101, v101, v105
	v_add_f32_e32 v169, 1.0, v169
	v_add_f32_e32 v170, 1.0, v170
	v_add_f32_e32 v171, 1.0, v171
	v_add_f32_e32 v172, 1.0, v172
	v_add_f32_e32 v173, 1.0, v173
	v_add_f32_e32 v174, 1.0, v174
	v_add_f32_e32 v175, 1.0, v175
	v_add_f32_e32 v176, 1.0, v176
	v_rcp_f32_e32 v169, v169
	v_rcp_f32_e32 v170, v170
	v_rcp_f32_e32 v171, v171
	v_rcp_f32_e32 v172, v172
	v_rcp_f32_e32 v173, v173
	v_rcp_f32_e32 v174, v174
	v_rcp_f32_e32 v175, v175
	v_rcp_f32_e32 v176, v176
	v_mul_f32_e32 v106, v106, v168
	v_mul_f32_e32 v107, v107, v168
	v_mul_f32_e32 v108, v108, v168
	v_mul_f32_e32 v109, v109, v168
	v_mul_f32_e32 v98, v98, v168
	v_mul_f32_e32 v99, v99, v168
	v_mul_f32_e32 v100, v100, v168
	v_mul_f32_e32 v101, v101, v168
	v_mul_f32_e32 v106, v106, v169
	v_mul_f32_e32 v107, v107, v170
	v_mul_f32_e32 v108, v108, v171
	v_mul_f32_e32 v109, v109, v172
	v_mul_f32_e32 v98, v98, v173
	v_mul_f32_e32 v99, v99, v174
	v_mul_f32_e32 v100, v100, v175
	v_mul_f32_e32 v101, v101, v176
	v_cvt_pk_bf16_f32 v184, v106, v107
	v_cvt_pk_bf16_f32 v185, v108, v109
	v_cvt_pk_bf16_f32 v186, v98, v99
	v_cvt_pk_bf16_f32 v187, v100, v101
	global_store_dwordx4 v[160:161], v[184:187], off nt
	v_add_co_u32_e32 v160, vcc, 0x16000, v160
	s_nop 1
	v_addc_co_u32_e32 v161, vcc, 0, v161, vcc
	s_waitcnt vmcnt(7)
	v_fmamk_f32 v166, v244, 0x3a800000, v194
	v_mul_f32_e32 v167, 0x4b800000, v166
	v_cmp_gt_f32_e32 vcc, s19, v166
	s_nop 1
	v_cndmask_b32_e32 v166, v166, v167, vcc
	v_rsq_f32_e32 v166, v166
	s_nop 0
	v_mul_f32_e32 v167, 0x45800000, v166
	v_cndmask_b32_e32 v166, v166, v167, vcc
	v_mul_f32_e32 v167, 0xbfb8aa3b, v166
	v_mul_f32_e32 v168, v166, v166
	v_mul_f32_e32 v169, v90, v167
	v_mul_f32_e32 v170, v91, v167
	v_mul_f32_e32 v171, v92, v167
	v_mul_f32_e32 v172, v93, v167
	v_mul_f32_e32 v173, v82, v167
	v_mul_f32_e32 v174, v83, v167
	v_mul_f32_e32 v175, v84, v167
	v_mul_f32_e32 v176, v85, v167
	v_exp_f32_e32 v169, v169
	v_exp_f32_e32 v170, v170
	v_exp_f32_e32 v171, v171
	v_exp_f32_e32 v172, v172
	v_exp_f32_e32 v173, v173
	v_exp_f32_e32 v174, v174
	v_exp_f32_e32 v175, v175
	v_exp_f32_e32 v176, v176
	v_mul_f32_e32 v90, v90, v94
	v_mul_f32_e32 v91, v91, v95
	v_mul_f32_e32 v92, v92, v96
	v_mul_f32_e32 v93, v93, v97
	v_mul_f32_e32 v82, v82, v86
	v_mul_f32_e32 v83, v83, v87
	v_mul_f32_e32 v84, v84, v88
	v_mul_f32_e32 v85, v85, v89
	v_add_f32_e32 v169, 1.0, v169
	v_add_f32_e32 v170, 1.0, v170
	v_add_f32_e32 v171, 1.0, v171
	v_add_f32_e32 v172, 1.0, v172
	v_add_f32_e32 v173, 1.0, v173
	v_add_f32_e32 v174, 1.0, v174
	v_add_f32_e32 v175, 1.0, v175
	v_add_f32_e32 v176, 1.0, v176
	v_rcp_f32_e32 v169, v169
	v_rcp_f32_e32 v170, v170
	v_rcp_f32_e32 v171, v171
	v_rcp_f32_e32 v172, v172
	v_rcp_f32_e32 v173, v173
	v_rcp_f32_e32 v174, v174
	v_rcp_f32_e32 v175, v175
	v_rcp_f32_e32 v176, v176
	v_mul_f32_e32 v90, v90, v168
	v_mul_f32_e32 v91, v91, v168
	v_mul_f32_e32 v92, v92, v168
	v_mul_f32_e32 v93, v93, v168
	v_mul_f32_e32 v82, v82, v168
	v_mul_f32_e32 v83, v83, v168
	v_mul_f32_e32 v84, v84, v168
	v_mul_f32_e32 v85, v85, v168
	v_mul_f32_e32 v90, v90, v169
	v_mul_f32_e32 v91, v91, v170
	v_mul_f32_e32 v92, v92, v171
	v_mul_f32_e32 v93, v93, v172
	v_mul_f32_e32 v82, v82, v173
	v_mul_f32_e32 v83, v83, v174
	v_mul_f32_e32 v84, v84, v175
	v_mul_f32_e32 v85, v85, v176
	v_cvt_pk_bf16_f32 v184, v90, v91
	v_cvt_pk_bf16_f32 v185, v92, v93
	v_cvt_pk_bf16_f32 v186, v82, v83
	v_cvt_pk_bf16_f32 v187, v84, v85
	global_store_dwordx4 v[160:161], v[184:187], off nt
	v_add_co_u32_e32 v160, vcc, 0x16000, v160
	s_nop 1
	v_addc_co_u32_e32 v161, vcc, 0, v161, vcc
	s_waitcnt vmcnt(7)
	v_fmamk_f32 v166, v245, 0x3a800000, v194
	v_mul_f32_e32 v167, 0x4b800000, v166
	v_cmp_gt_f32_e32 vcc, s19, v166
	s_nop 1
	v_cndmask_b32_e32 v166, v166, v167, vcc
	v_rsq_f32_e32 v166, v166
	s_nop 0
	v_mul_f32_e32 v167, 0x45800000, v166
	v_cndmask_b32_e32 v166, v166, v167, vcc
	v_mul_f32_e32 v167, 0xbfb8aa3b, v166
	v_mul_f32_e32 v168, v166, v166
	v_mul_f32_e32 v169, v68, v167
	v_mul_f32_e32 v170, v69, v167
	v_mul_f32_e32 v171, v70, v167
	v_mul_f32_e32 v172, v71, v167
	v_mul_f32_e32 v173, v64, v167
	v_mul_f32_e32 v174, v65, v167
	v_mul_f32_e32 v175, v66, v167
	v_mul_f32_e32 v176, v67, v167
	v_exp_f32_e32 v169, v169
	v_exp_f32_e32 v170, v170
	v_exp_f32_e32 v171, v171
	v_exp_f32_e32 v172, v172
	v_exp_f32_e32 v173, v173
	v_exp_f32_e32 v174, v174
	v_exp_f32_e32 v175, v175
	v_exp_f32_e32 v176, v176
	v_mul_f32_e32 v68, v68, v76
	v_mul_f32_e32 v69, v69, v77
	v_mul_f32_e32 v70, v70, v78
	v_mul_f32_e32 v71, v71, v79
	v_mul_f32_e32 v64, v64, v72
	v_mul_f32_e32 v65, v65, v73
	v_mul_f32_e32 v66, v66, v74
	v_mul_f32_e32 v67, v67, v75
	v_add_f32_e32 v169, 1.0, v169
	v_add_f32_e32 v170, 1.0, v170
	v_add_f32_e32 v171, 1.0, v171
	v_add_f32_e32 v172, 1.0, v172
	v_add_f32_e32 v173, 1.0, v173
	v_add_f32_e32 v174, 1.0, v174
	v_add_f32_e32 v175, 1.0, v175
	v_add_f32_e32 v176, 1.0, v176
	v_rcp_f32_e32 v169, v169
	v_rcp_f32_e32 v170, v170
	v_rcp_f32_e32 v171, v171
	v_rcp_f32_e32 v172, v172
	v_rcp_f32_e32 v173, v173
	v_rcp_f32_e32 v174, v174
	v_rcp_f32_e32 v175, v175
	v_rcp_f32_e32 v176, v176
	v_mul_f32_e32 v68, v68, v168
	v_mul_f32_e32 v69, v69, v168
	v_mul_f32_e32 v70, v70, v168
	v_mul_f32_e32 v71, v71, v168
	v_mul_f32_e32 v64, v64, v168
	v_mul_f32_e32 v65, v65, v168
	v_mul_f32_e32 v66, v66, v168
	v_mul_f32_e32 v67, v67, v168
	v_mul_f32_e32 v68, v68, v169
	v_mul_f32_e32 v69, v69, v170
	v_mul_f32_e32 v70, v70, v171
	v_mul_f32_e32 v71, v71, v172
	v_mul_f32_e32 v64, v64, v173
	v_mul_f32_e32 v65, v65, v174
	v_mul_f32_e32 v66, v66, v175
	v_mul_f32_e32 v67, v67, v176
	v_cvt_pk_bf16_f32 v184, v68, v69
	v_cvt_pk_bf16_f32 v185, v70, v71
	v_cvt_pk_bf16_f32 v186, v64, v65
	v_cvt_pk_bf16_f32 v187, v66, v67
	global_store_dwordx4 v[160:161], v[184:187], off nt
	v_add_co_u32_e32 v160, vcc, 0x6e000, v160
	s_nop 1
	v_addc_co_u32_e32 v161, vcc, 0, v161, vcc
	s_waitcnt vmcnt(7)
	v_fmamk_f32 v166, v246, 0x3a800000, v194
	v_mul_f32_e32 v167, 0x4b800000, v166
	v_cmp_gt_f32_e32 vcc, s19, v166
	s_nop 1
	v_cndmask_b32_e32 v166, v166, v167, vcc
	v_rsq_f32_e32 v166, v166
	s_nop 0
	v_mul_f32_e32 v167, 0x45800000, v166
	v_cndmask_b32_e32 v166, v166, v167, vcc
	v_mul_f32_e32 v167, 0xbfb8aa3b, v166
	v_mul_f32_e32 v168, v166, v166
	v_mul_f32_e32 v169, v52, v167
	v_mul_f32_e32 v170, v53, v167
	v_mul_f32_e32 v171, v54, v167
	v_mul_f32_e32 v172, v55, v167
	v_mul_f32_e32 v173, v48, v167
	v_mul_f32_e32 v174, v49, v167
	v_mul_f32_e32 v175, v50, v167
	v_mul_f32_e32 v176, v51, v167
	v_exp_f32_e32 v169, v169
	v_exp_f32_e32 v170, v170
	v_exp_f32_e32 v171, v171
	v_exp_f32_e32 v172, v172
	v_exp_f32_e32 v173, v173
	v_exp_f32_e32 v174, v174
	v_exp_f32_e32 v175, v175
	v_exp_f32_e32 v176, v176
	v_mul_f32_e32 v52, v52, v60
	v_mul_f32_e32 v53, v53, v61
	v_mul_f32_e32 v54, v54, v62
	v_mul_f32_e32 v55, v55, v63
	v_mul_f32_e32 v48, v48, v56
	v_mul_f32_e32 v49, v49, v57
	v_mul_f32_e32 v50, v50, v58
	v_mul_f32_e32 v51, v51, v59
	v_add_f32_e32 v169, 1.0, v169
	v_add_f32_e32 v170, 1.0, v170
	v_add_f32_e32 v171, 1.0, v171
	v_add_f32_e32 v172, 1.0, v172
	v_add_f32_e32 v173, 1.0, v173
	v_add_f32_e32 v174, 1.0, v174
	v_add_f32_e32 v175, 1.0, v175
	v_add_f32_e32 v176, 1.0, v176
	v_rcp_f32_e32 v169, v169
	v_rcp_f32_e32 v170, v170
	v_rcp_f32_e32 v171, v171
	v_rcp_f32_e32 v172, v172
	v_rcp_f32_e32 v173, v173
	v_rcp_f32_e32 v174, v174
	v_rcp_f32_e32 v175, v175
	v_rcp_f32_e32 v176, v176
	v_mul_f32_e32 v52, v52, v168
	v_mul_f32_e32 v53, v53, v168
	v_mul_f32_e32 v54, v54, v168
	v_mul_f32_e32 v55, v55, v168
	v_mul_f32_e32 v48, v48, v168
	v_mul_f32_e32 v49, v49, v168
	v_mul_f32_e32 v50, v50, v168
	v_mul_f32_e32 v51, v51, v168
	v_mul_f32_e32 v52, v52, v169
	v_mul_f32_e32 v53, v53, v170
	v_mul_f32_e32 v54, v54, v171
	v_mul_f32_e32 v55, v55, v172
	v_mul_f32_e32 v48, v48, v173
	v_mul_f32_e32 v49, v49, v174
	v_mul_f32_e32 v50, v50, v175
	v_mul_f32_e32 v51, v51, v176
	v_cvt_pk_bf16_f32 v184, v52, v53
	v_cvt_pk_bf16_f32 v185, v54, v55
	v_cvt_pk_bf16_f32 v186, v48, v49
	v_cvt_pk_bf16_f32 v187, v50, v51
	global_store_dwordx4 v[160:161], v[184:187], off nt
	v_add_co_u32_e32 v160, vcc, 0x16000, v160
	s_nop 1
	v_addc_co_u32_e32 v161, vcc, 0, v161, vcc
	s_waitcnt vmcnt(7)
	v_fmamk_f32 v166, v247, 0x3a800000, v194
	v_mul_f32_e32 v167, 0x4b800000, v166
	v_cmp_gt_f32_e32 vcc, s19, v166
	s_nop 1
	v_cndmask_b32_e32 v166, v166, v167, vcc
	v_rsq_f32_e32 v166, v166
	s_nop 0
	v_mul_f32_e32 v167, 0x45800000, v166
	v_cndmask_b32_e32 v166, v166, v167, vcc
	v_mul_f32_e32 v167, 0xbfb8aa3b, v166
	v_mul_f32_e32 v168, v166, v166
	v_mul_f32_e32 v169, v36, v167
	v_mul_f32_e32 v170, v37, v167
	v_mul_f32_e32 v171, v38, v167
	v_mul_f32_e32 v172, v39, v167
	v_mul_f32_e32 v173, v32, v167
	v_mul_f32_e32 v174, v33, v167
	v_mul_f32_e32 v175, v34, v167
	v_mul_f32_e32 v176, v35, v167
	v_exp_f32_e32 v169, v169
	v_exp_f32_e32 v170, v170
	v_exp_f32_e32 v171, v171
	v_exp_f32_e32 v172, v172
	v_exp_f32_e32 v173, v173
	v_exp_f32_e32 v174, v174
	v_exp_f32_e32 v175, v175
	v_exp_f32_e32 v176, v176
	v_mul_f32_e32 v36, v36, v44
	v_mul_f32_e32 v37, v37, v45
	v_mul_f32_e32 v38, v38, v46
	v_mul_f32_e32 v39, v39, v47
	v_mul_f32_e32 v32, v32, v40
	v_mul_f32_e32 v33, v33, v41
	v_mul_f32_e32 v34, v34, v42
	v_mul_f32_e32 v35, v35, v43
	v_add_f32_e32 v169, 1.0, v169
	v_add_f32_e32 v170, 1.0, v170
	v_add_f32_e32 v171, 1.0, v171
	v_add_f32_e32 v172, 1.0, v172
	v_add_f32_e32 v173, 1.0, v173
	v_add_f32_e32 v174, 1.0, v174
	v_add_f32_e32 v175, 1.0, v175
	v_add_f32_e32 v176, 1.0, v176
	v_rcp_f32_e32 v169, v169
	v_rcp_f32_e32 v170, v170
	v_rcp_f32_e32 v171, v171
	v_rcp_f32_e32 v172, v172
	v_rcp_f32_e32 v173, v173
	v_rcp_f32_e32 v174, v174
	v_rcp_f32_e32 v175, v175
	v_rcp_f32_e32 v176, v176
	v_mul_f32_e32 v36, v36, v168
	v_mul_f32_e32 v37, v37, v168
	v_mul_f32_e32 v38, v38, v168
	v_mul_f32_e32 v39, v39, v168
	v_mul_f32_e32 v32, v32, v168
	v_mul_f32_e32 v33, v33, v168
	v_mul_f32_e32 v34, v34, v168
	v_mul_f32_e32 v35, v35, v168
	v_mul_f32_e32 v36, v36, v169
	v_mul_f32_e32 v37, v37, v170
	v_mul_f32_e32 v38, v38, v171
	v_mul_f32_e32 v39, v39, v172
	v_mul_f32_e32 v32, v32, v173
	v_mul_f32_e32 v33, v33, v174
	v_mul_f32_e32 v34, v34, v175
	v_mul_f32_e32 v35, v35, v176
	v_cvt_pk_bf16_f32 v184, v36, v37
	v_cvt_pk_bf16_f32 v185, v38, v39
	v_cvt_pk_bf16_f32 v186, v32, v33
	v_cvt_pk_bf16_f32 v187, v34, v35
	global_store_dwordx4 v[160:161], v[184:187], off nt
	v_add_co_u32_e32 v160, vcc, 0x16000, v160
	s_nop 1
	v_addc_co_u32_e32 v161, vcc, 0, v161, vcc
	s_waitcnt vmcnt(7)
	v_fmamk_f32 v166, v248, 0x3a800000, v194
	v_mul_f32_e32 v167, 0x4b800000, v166
	v_cmp_gt_f32_e32 vcc, s19, v166
	s_nop 1
	v_cndmask_b32_e32 v166, v166, v167, vcc
	v_rsq_f32_e32 v166, v166
	s_nop 0
	v_mul_f32_e32 v167, 0x45800000, v166
	v_cndmask_b32_e32 v166, v166, v167, vcc
	v_mul_f32_e32 v167, 0xbfb8aa3b, v166
	v_mul_f32_e32 v168, v166, v166
	v_mul_f32_e32 v169, v20, v167
	v_mul_f32_e32 v170, v21, v167
	v_mul_f32_e32 v171, v22, v167
	v_mul_f32_e32 v172, v23, v167
	v_mul_f32_e32 v173, v16, v167
	v_mul_f32_e32 v174, v17, v167
	v_mul_f32_e32 v175, v18, v167
	v_mul_f32_e32 v176, v19, v167
	v_exp_f32_e32 v169, v169
	v_exp_f32_e32 v170, v170
	v_exp_f32_e32 v171, v171
	v_exp_f32_e32 v172, v172
	v_exp_f32_e32 v173, v173
	v_exp_f32_e32 v174, v174
	v_exp_f32_e32 v175, v175
	v_exp_f32_e32 v176, v176
	v_mul_f32_e32 v20, v20, v28
	v_mul_f32_e32 v21, v21, v29
	v_mul_f32_e32 v22, v22, v30
	v_mul_f32_e32 v23, v23, v31
	v_mul_f32_e32 v16, v16, v24
	v_mul_f32_e32 v17, v17, v25
	v_mul_f32_e32 v18, v18, v26
	v_mul_f32_e32 v19, v19, v27
	v_add_f32_e32 v169, 1.0, v169
	v_add_f32_e32 v170, 1.0, v170
	v_add_f32_e32 v171, 1.0, v171
	v_add_f32_e32 v172, 1.0, v172
	v_add_f32_e32 v173, 1.0, v173
	v_add_f32_e32 v174, 1.0, v174
	v_add_f32_e32 v175, 1.0, v175
	v_add_f32_e32 v176, 1.0, v176
	v_rcp_f32_e32 v169, v169
	v_rcp_f32_e32 v170, v170
	v_rcp_f32_e32 v171, v171
	v_rcp_f32_e32 v172, v172
	v_rcp_f32_e32 v173, v173
	v_rcp_f32_e32 v174, v174
	v_rcp_f32_e32 v175, v175
	v_rcp_f32_e32 v176, v176
	v_mul_f32_e32 v20, v20, v168
	v_mul_f32_e32 v21, v21, v168
	v_mul_f32_e32 v22, v22, v168
	v_mul_f32_e32 v23, v23, v168
	v_mul_f32_e32 v16, v16, v168
	v_mul_f32_e32 v17, v17, v168
	v_mul_f32_e32 v18, v18, v168
	v_mul_f32_e32 v19, v19, v168
	v_mul_f32_e32 v20, v20, v169
	v_mul_f32_e32 v21, v21, v170
	v_mul_f32_e32 v22, v22, v171
	v_mul_f32_e32 v23, v23, v172
	v_mul_f32_e32 v16, v16, v173
	v_mul_f32_e32 v17, v17, v174
	v_mul_f32_e32 v18, v18, v175
	v_mul_f32_e32 v19, v19, v176
	v_cvt_pk_bf16_f32 v184, v20, v21
	v_cvt_pk_bf16_f32 v185, v22, v23
	v_cvt_pk_bf16_f32 v186, v16, v17
	v_cvt_pk_bf16_f32 v187, v18, v19
	global_store_dwordx4 v[160:161], v[184:187], off nt
	v_add_co_u32_e32 v160, vcc, 0x16000, v160
	s_nop 1
	v_addc_co_u32_e32 v161, vcc, 0, v161, vcc
	s_waitcnt vmcnt(7)
	v_fmamk_f32 v166, v249, 0x3a800000, v194
	v_mul_f32_e32 v167, 0x4b800000, v166
	v_cmp_gt_f32_e32 vcc, s19, v166
	s_nop 1
	v_cndmask_b32_e32 v166, v166, v167, vcc
	v_rsq_f32_e32 v166, v166
	s_nop 0
	v_mul_f32_e32 v167, 0x45800000, v166
	v_cndmask_b32_e32 v166, v166, v167, vcc
	v_mul_f32_e32 v167, 0xbfb8aa3b, v166
	v_mul_f32_e32 v168, v166, v166
	v_mul_f32_e32 v169, v8, v167
	v_mul_f32_e32 v170, v9, v167
	v_mul_f32_e32 v171, v10, v167
	v_mul_f32_e32 v172, v11, v167
	v_mul_f32_e32 v173, v0, v167
	v_mul_f32_e32 v174, v1, v167
	v_mul_f32_e32 v175, v2, v167
	v_mul_f32_e32 v176, v3, v167
	v_exp_f32_e32 v169, v169
	v_exp_f32_e32 v170, v170
	v_exp_f32_e32 v171, v171
	v_exp_f32_e32 v172, v172
	v_exp_f32_e32 v173, v173
	v_exp_f32_e32 v174, v174
	v_exp_f32_e32 v175, v175
	v_exp_f32_e32 v176, v176
	v_mul_f32_e32 v8, v8, v12
	v_mul_f32_e32 v9, v9, v13
	v_mul_f32_e32 v10, v10, v14
	v_mul_f32_e32 v11, v11, v15
	v_mul_f32_e32 v0, v0, v4
	v_mul_f32_e32 v1, v1, v5
	v_mul_f32_e32 v2, v2, v6
	v_mul_f32_e32 v3, v3, v7
	v_add_f32_e32 v169, 1.0, v169
	v_add_f32_e32 v170, 1.0, v170
	v_add_f32_e32 v171, 1.0, v171
	v_add_f32_e32 v172, 1.0, v172
	v_add_f32_e32 v173, 1.0, v173
	v_add_f32_e32 v174, 1.0, v174
	v_add_f32_e32 v175, 1.0, v175
	v_add_f32_e32 v176, 1.0, v176
	v_rcp_f32_e32 v169, v169
	v_rcp_f32_e32 v170, v170
	v_rcp_f32_e32 v171, v171
	v_rcp_f32_e32 v172, v172
	v_rcp_f32_e32 v173, v173
	v_rcp_f32_e32 v174, v174
	v_rcp_f32_e32 v175, v175
	v_rcp_f32_e32 v176, v176
	v_mul_f32_e32 v8, v8, v168
	v_mul_f32_e32 v9, v9, v168
	v_mul_f32_e32 v10, v10, v168
	v_mul_f32_e32 v11, v11, v168
	v_mul_f32_e32 v0, v0, v168
	v_mul_f32_e32 v1, v1, v168
	v_mul_f32_e32 v2, v2, v168
	v_mul_f32_e32 v3, v3, v168
	v_mul_f32_e32 v8, v8, v169
	v_mul_f32_e32 v9, v9, v170
	v_mul_f32_e32 v10, v10, v171
	v_mul_f32_e32 v11, v11, v172
	v_mul_f32_e32 v0, v0, v173
	v_mul_f32_e32 v1, v1, v174
	v_mul_f32_e32 v2, v2, v175
	v_mul_f32_e32 v3, v3, v176
	v_cvt_pk_bf16_f32 v184, v8, v9
	v_cvt_pk_bf16_f32 v185, v10, v11
	v_cvt_pk_bf16_f32 v186, v0, v1
	v_cvt_pk_bf16_f32 v187, v2, v3
	global_store_dwordx4 v[160:161], v[184:187], off nt
	s_andn2_b64 vcc, exec, s[44:45]
	s_mov_b64 s[44:45], -1
	s_cbranch_vccnz .LBB0_223
	s_andn2_b64 vcc, exec, s[0:1]
	s_cbranch_vccnz .LBB0_222
	s_barrier
	s_branch .LBB0_222

.LBB0_677:
	s_add_u32 s48, s46, 0xfffc0080
	s_addc_u32 s49, s47, -1
	s_add_i32 s61, 16, 0x10000
	s_cmp_eq_u32 s60, 12
	s_cselect_b32 s51, s15, s49
	s_cselect_b32 s50, s54, s48
	v_add_u32_e32 v80, s61, v146
	s_cselect_b32 s49, s11, s57
	s_cselect_b32 s48, s55, s56
	s_add_i32 s74, 16, 0x14000
	ds_read_b128 v[142:145], v80
	ds_read_b128 v[148:151], v80 offset:1024
	ds_read_b128 v[160:163], v80 offset:2048
	ds_read_b128 v[164:167], v80 offset:3072
	v_add_u32_e32 v80, s74, v146
	ds_read_b128 v[168:171], v80
	ds_read_b128 v[172:175], v80 offset:1024
	ds_read_b128 v[176:179], v80 offset:2048
	ds_read_b128 v[180:183], v80 offset:3072
	v_lshl_add_u64 v[208:209], s[46:47], 0, v[138:139]
	s_add_i32 m0, s13, 0xc000
	ds_read_b128 v[184:187], v147
	ds_read_b128 v[188:191], v147 offset:1024
	ds_read_b128 v[204:207], v147 offset:2048
	ds_read_b128 v[214:217], v147 offset:3072
	ds_read_b128 v[218:221], v147 offset:4096
	ds_read_b128 v[222:225], v147 offset:5120
	ds_read_b128 v[226:229], v147 offset:6144
	ds_read_b128 v[230:233], v147 offset:7168
	global_load_lds_dwordx4 v[208:209], off
	v_lshl_add_u64 v[208:209], s[46:47], 0, v[140:141]
	s_add_i32 m0, s13, 0xe000
	s_nop 0
	global_load_lds_dwordx4 v[208:209], off
	s_waitcnt vmcnt(8)
	s_waitcnt lgkmcnt(0)
	s_barrier
	s_waitcnt lgkmcnt(0)
	v_mfma_f32_16x16x32_bf16 v[126:129], v[142:145], v[184:187], v[126:129]
	v_mfma_f32_16x16x32_bf16 v[118:121], v[160:163], v[184:187], v[118:121]
	v_mfma_f32_16x16x32_bf16 v[110:113], v[142:145], v[204:207], v[110:113]
	v_mfma_f32_16x16x32_bf16 v[102:105], v[160:163], v[204:207], v[102:105]
	v_mfma_f32_16x16x32_bf16 v[94:97], v[142:145], v[218:221], v[94:97]
	v_mfma_f32_16x16x32_bf16 v[86:89], v[160:163], v[218:221], v[86:89]
	v_mfma_f32_16x16x32_bf16 v[76:79], v[142:145], v[226:229], v[76:79]
	v_mfma_f32_16x16x32_bf16 v[68:71], v[160:163], v[226:229], v[68:71]
	v_mfma_f32_16x16x32_bf16 v[126:129], v[148:151], v[188:191], v[126:129]
	v_mfma_f32_16x16x32_bf16 v[118:121], v[164:167], v[188:191], v[118:121]
	v_mfma_f32_16x16x32_bf16 v[110:113], v[148:151], v[214:217], v[110:113]
	v_mfma_f32_16x16x32_bf16 v[102:105], v[164:167], v[214:217], v[102:105]
	v_mfma_f32_16x16x32_bf16 v[94:97], v[148:151], v[222:225], v[94:97]
	v_mfma_f32_16x16x32_bf16 v[86:89], v[164:167], v[222:225], v[86:89]
	v_mfma_f32_16x16x32_bf16 v[76:79], v[148:151], v[230:233], v[76:79]
	v_mfma_f32_16x16x32_bf16 v[68:71], v[164:167], v[230:233], v[68:71]
	v_mfma_f32_16x16x32_bf16 v[122:125], v[168:171], v[184:187], v[122:125]
	v_mfma_f32_16x16x32_bf16 v[114:117], v[176:179], v[184:187], v[114:117]
	v_mfma_f32_16x16x32_bf16 v[106:109], v[168:171], v[204:207], v[106:109]
	v_mfma_f32_16x16x32_bf16 v[98:101], v[176:179], v[204:207], v[98:101]
	v_mfma_f32_16x16x32_bf16 v[90:93], v[168:171], v[218:221], v[90:93]
	v_mfma_f32_16x16x32_bf16 v[82:85], v[176:179], v[218:221], v[82:85]
	v_mfma_f32_16x16x32_bf16 v[72:75], v[168:171], v[226:229], v[72:75]
	v_mfma_f32_16x16x32_bf16 v[64:67], v[176:179], v[226:229], v[64:67]
	v_mfma_f32_16x16x32_bf16 v[122:125], v[172:175], v[188:191], v[122:125]
	v_mfma_f32_16x16x32_bf16 v[114:117], v[180:183], v[188:191], v[114:117]
	v_mfma_f32_16x16x32_bf16 v[106:109], v[172:175], v[214:217], v[106:109]
	v_mfma_f32_16x16x32_bf16 v[98:101], v[180:183], v[214:217], v[98:101]
	v_mfma_f32_16x16x32_bf16 v[90:93], v[172:175], v[222:225], v[90:93]
	v_mfma_f32_16x16x32_bf16 v[82:85], v[180:183], v[222:225], v[82:85]
	v_mfma_f32_16x16x32_bf16 v[72:75], v[172:175], v[230:233], v[72:75]
	v_mfma_f32_16x16x32_bf16 v[64:67], v[180:183], v[230:233], v[64:67]
	s_barrier
	s_add_i32 s61, s61, s4
	v_lshl_add_u64 v[208:209], s[48:49], 0, v[134:135]
	s_mov_b32 m0, s61
	ds_read_b128 v[184:187], v147 offset:16384
	ds_read_b128 v[188:191], v147 offset:17408
	ds_read_b128 v[204:207], v147 offset:18432
	ds_read_b128 v[214:217], v147 offset:19456
	ds_read_b128 v[218:221], v147 offset:20480
	ds_read_b128 v[222:225], v147 offset:21504
	ds_read_b128 v[226:229], v147 offset:22528
	ds_read_b128 v[230:233], v147 offset:23552
	global_load_lds_dwordx4 v[208:209], off
	s_add_i32 m0, s61, 0x2000
	s_add_u32 s66, s48, 0x40000
	v_lshl_add_u64 v[234:235], s[48:49], 0, v[130:131]
	s_addc_u32 s67, s49, 0
	s_add_i32 s61, s74, s4
	global_load_lds_dwordx4 v[234:235], off
	v_lshl_add_u64 v[236:237], s[66:67], 0, v[134:135]
	s_mov_b32 m0, s61
	v_lshl_add_u64 v[238:239], s[50:51], 0, v[132:133]
	global_load_lds_dwordx4 v[236:237], off
	v_lshl_add_u64 v[236:237], s[66:67], 0, v[130:131]
	s_add_i32 m0, s61, 0x2000
	s_nop 0
	global_load_lds_dwordx4 v[236:237], off
	v_lshl_add_u64 v[236:237], s[50:51], 0, v[136:137]
	s_mov_b32 m0, s13
	s_nop 0
	global_load_lds_dwordx4 v[236:237], off
	s_mov_b32 m0, s25
	s_nop 0
	global_load_lds_dwordx4 v[238:239], off
	s_waitcnt vmcnt(8)
	s_waitcnt lgkmcnt(0)
	s_barrier
	s_waitcnt lgkmcnt(0)
	v_mfma_f32_16x16x32_bf16 v[60:63], v[142:145], v[184:187], v[60:63]
	v_mfma_f32_16x16x32_bf16 v[52:55], v[160:163], v[184:187], v[52:55]
	v_mfma_f32_16x16x32_bf16 v[44:47], v[142:145], v[204:207], v[44:47]
	v_mfma_f32_16x16x32_bf16 v[36:39], v[160:163], v[204:207], v[36:39]
	v_mfma_f32_16x16x32_bf16 v[28:31], v[142:145], v[218:221], v[28:31]
	v_mfma_f32_16x16x32_bf16 v[20:23], v[160:163], v[218:221], v[20:23]
	v_mfma_f32_16x16x32_bf16 v[12:15], v[142:145], v[226:229], v[12:15]
	v_mfma_f32_16x16x32_bf16 v[4:7], v[160:163], v[226:229], v[4:7]
	v_mfma_f32_16x16x32_bf16 v[60:63], v[148:151], v[188:191], v[60:63]
	v_mfma_f32_16x16x32_bf16 v[52:55], v[164:167], v[188:191], v[52:55]
	v_mfma_f32_16x16x32_bf16 v[44:47], v[148:151], v[214:217], v[44:47]
	v_mfma_f32_16x16x32_bf16 v[36:39], v[164:167], v[214:217], v[36:39]
	v_mfma_f32_16x16x32_bf16 v[28:31], v[148:151], v[222:225], v[28:31]
	v_mfma_f32_16x16x32_bf16 v[20:23], v[164:167], v[222:225], v[20:23]
	v_mfma_f32_16x16x32_bf16 v[12:15], v[148:151], v[230:233], v[12:15]
	v_mfma_f32_16x16x32_bf16 v[4:7], v[164:167], v[230:233], v[4:7]
	v_mfma_f32_16x16x32_bf16 v[56:59], v[168:171], v[184:187], v[56:59]
	v_mfma_f32_16x16x32_bf16 v[48:51], v[176:179], v[184:187], v[48:51]
	v_mfma_f32_16x16x32_bf16 v[40:43], v[168:171], v[204:207], v[40:43]
	v_mfma_f32_16x16x32_bf16 v[32:35], v[176:179], v[204:207], v[32:35]
	v_mfma_f32_16x16x32_bf16 v[24:27], v[168:171], v[218:221], v[24:27]
	v_mfma_f32_16x16x32_bf16 v[16:19], v[176:179], v[218:221], v[16:19]
	v_mfma_f32_16x16x32_bf16 v[8:11], v[168:171], v[226:229], v[8:11]
	v_mfma_f32_16x16x32_bf16 v[0:3], v[176:179], v[226:229], v[0:3]
	v_mfma_f32_16x16x32_bf16 v[56:59], v[172:175], v[188:191], v[56:59]
	v_mfma_f32_16x16x32_bf16 v[48:51], v[180:183], v[188:191], v[48:51]
	v_mfma_f32_16x16x32_bf16 v[40:43], v[172:175], v[214:217], v[40:43]
	v_mfma_f32_16x16x32_bf16 v[32:35], v[180:183], v[214:217], v[32:35]
	v_mfma_f32_16x16x32_bf16 v[24:27], v[172:175], v[222:225], v[24:27]
	v_mfma_f32_16x16x32_bf16 v[16:19], v[180:183], v[222:225], v[16:19]
	v_mfma_f32_16x16x32_bf16 v[8:11], v[172:175], v[230:233], v[8:11]
	v_mfma_f32_16x16x32_bf16 v[0:3], v[180:183], v[230:233], v[0:3]
	s_barrier
	s_add_i32 s61, 16, 0x18000
	v_add_u32_e32 v80, s61, v146
	s_add_i32 s66, 16, 0x1c000
	ds_read_b128 v[142:145], v80
	ds_read_b128 v[148:151], v80 offset:1024
	ds_read_b128 v[160:163], v80 offset:2048
	ds_read_b128 v[164:167], v80 offset:3072
	v_add_u32_e32 v80, s66, v146
	ds_read_b128 v[168:171], v80
	ds_read_b128 v[172:175], v80 offset:1024
	ds_read_b128 v[176:179], v80 offset:2048
	ds_read_b128 v[180:183], v80 offset:3072
	s_add_u32 s50, s50, 0x40000
	s_addc_u32 s51, s51, 0
	s_mov_b32 m0, s30
	v_lshl_add_u64 v[240:241], s[50:51], 0, v[136:137]
	ds_read_b128 v[184:187], v147 offset:32768
	ds_read_b128 v[188:191], v147 offset:33792
	ds_read_b128 v[204:207], v147 offset:34816
	ds_read_b128 v[214:217], v147 offset:35840
	ds_read_b128 v[218:221], v147 offset:36864
	ds_read_b128 v[222:225], v147 offset:37888
	ds_read_b128 v[226:229], v147 offset:38912
	ds_read_b128 v[230:233], v147 offset:39936
	global_load_lds_dwordx4 v[240:241], off
	v_lshl_add_u64 v[240:241], s[50:51], 0, v[132:133]
	s_mov_b32 m0, s33
	s_nop 0
	global_load_lds_dwordx4 v[240:241], off
	s_waitcnt vmcnt(8)
	s_waitcnt lgkmcnt(0)
	s_barrier
	s_waitcnt lgkmcnt(0)
	v_mfma_f32_16x16x32_bf16 v[126:129], v[142:145], v[184:187], v[126:129]
	v_mfma_f32_16x16x32_bf16 v[118:121], v[160:163], v[184:187], v[118:121]
	v_mfma_f32_16x16x32_bf16 v[110:113], v[142:145], v[204:207], v[110:113]
	v_mfma_f32_16x16x32_bf16 v[102:105], v[160:163], v[204:207], v[102:105]
	v_mfma_f32_16x16x32_bf16 v[94:97], v[142:145], v[218:221], v[94:97]
	v_mfma_f32_16x16x32_bf16 v[86:89], v[160:163], v[218:221], v[86:89]
	v_mfma_f32_16x16x32_bf16 v[76:79], v[142:145], v[226:229], v[76:79]
	v_mfma_f32_16x16x32_bf16 v[68:71], v[160:163], v[226:229], v[68:71]
	v_mfma_f32_16x16x32_bf16 v[126:129], v[148:151], v[188:191], v[126:129]
	v_mfma_f32_16x16x32_bf16 v[118:121], v[164:167], v[188:191], v[118:121]
	v_mfma_f32_16x16x32_bf16 v[110:113], v[148:151], v[214:217], v[110:113]
	v_mfma_f32_16x16x32_bf16 v[102:105], v[164:167], v[214:217], v[102:105]
	v_mfma_f32_16x16x32_bf16 v[94:97], v[148:151], v[222:225], v[94:97]
	v_mfma_f32_16x16x32_bf16 v[86:89], v[164:167], v[222:225], v[86:89]
	v_mfma_f32_16x16x32_bf16 v[76:79], v[148:151], v[230:233], v[76:79]
	v_mfma_f32_16x16x32_bf16 v[68:71], v[164:167], v[230:233], v[68:71]
	v_mfma_f32_16x16x32_bf16 v[122:125], v[168:171], v[184:187], v[122:125]
	v_mfma_f32_16x16x32_bf16 v[114:117], v[176:179], v[184:187], v[114:117]
	v_mfma_f32_16x16x32_bf16 v[106:109], v[168:171], v[204:207], v[106:109]
	v_mfma_f32_16x16x32_bf16 v[98:101], v[176:179], v[204:207], v[98:101]
	v_mfma_f32_16x16x32_bf16 v[90:93], v[168:171], v[218:221], v[90:93]
	v_mfma_f32_16x16x32_bf16 v[82:85], v[176:179], v[218:221], v[82:85]
	v_mfma_f32_16x16x32_bf16 v[72:75], v[168:171], v[226:229], v[72:75]
	v_mfma_f32_16x16x32_bf16 v[64:67], v[176:179], v[226:229], v[64:67]
	v_mfma_f32_16x16x32_bf16 v[122:125], v[172:175], v[188:191], v[122:125]
	v_mfma_f32_16x16x32_bf16 v[114:117], v[180:183], v[188:191], v[114:117]
	v_mfma_f32_16x16x32_bf16 v[106:109], v[172:175], v[214:217], v[106:109]
	v_mfma_f32_16x16x32_bf16 v[98:101], v[180:183], v[214:217], v[98:101]
	v_mfma_f32_16x16x32_bf16 v[90:93], v[172:175], v[222:225], v[90:93]
	v_mfma_f32_16x16x32_bf16 v[82:85], v[180:183], v[222:225], v[82:85]
	v_mfma_f32_16x16x32_bf16 v[72:75], v[172:175], v[230:233], v[72:75]
	v_mfma_f32_16x16x32_bf16 v[64:67], v[180:183], v[230:233], v[64:67]
	s_barrier
	s_add_i32 s50, s61, s4
	v_lshl_add_u64 v[208:209], v[208:209], 0, s[20:21]
	s_mov_b32 m0, s50
	ds_read_b128 v[184:187], v147 offset:49152
	ds_read_b128 v[188:191], v147 offset:50176
	ds_read_b128 v[204:207], v147 offset:51200
	ds_read_b128 v[214:217], v147 offset:52224
	ds_read_b128 v[218:221], v147 offset:53248
	ds_read_b128 v[222:225], v147 offset:54272
	ds_read_b128 v[226:229], v147 offset:55296
	ds_read_b128 v[230:233], v147 offset:56320
	global_load_lds_dwordx4 v[208:209], off
	s_add_i32 m0, s50, 0x2000
	s_add_u32 s48, s48, 0x40080
	v_lshl_add_u64 v[208:209], v[234:235], 0, s[20:21]
	s_addc_u32 s49, s49, 0
	s_add_i32 s50, s66, s4
	global_load_lds_dwordx4 v[208:209], off
	v_lshl_add_u64 v[208:209], s[48:49], 0, v[134:135]
	s_mov_b32 m0, s50
	s_nop 0
	global_load_lds_dwordx4 v[208:209], off
	v_lshl_add_u64 v[208:209], s[48:49], 0, v[130:131]
	s_add_i32 m0, s50, 0x2000
	s_nop 0
	global_load_lds_dwordx4 v[208:209], off
	v_lshl_add_u64 v[208:209], v[236:237], 0, s[20:21]
	s_mov_b32 m0, s34
	s_nop 0
	global_load_lds_dwordx4 v[208:209], off
	v_lshl_add_u64 v[208:209], v[238:239], 0, s[20:21]
	s_mov_b32 m0, s36
	s_nop 0
	global_load_lds_dwordx4 v[208:209], off
	s_waitcnt vmcnt(8)
	s_waitcnt lgkmcnt(0)
	s_barrier
	s_waitcnt lgkmcnt(0)
	v_mfma_f32_16x16x32_bf16 v[60:63], v[142:145], v[184:187], v[60:63]
	v_mfma_f32_16x16x32_bf16 v[52:55], v[160:163], v[184:187], v[52:55]
	v_mfma_f32_16x16x32_bf16 v[44:47], v[142:145], v[204:207], v[44:47]
	v_mfma_f32_16x16x32_bf16 v[36:39], v[160:163], v[204:207], v[36:39]
	v_mfma_f32_16x16x32_bf16 v[28:31], v[142:145], v[218:221], v[28:31]
	v_mfma_f32_16x16x32_bf16 v[20:23], v[160:163], v[218:221], v[20:23]
	v_mfma_f32_16x16x32_bf16 v[12:15], v[142:145], v[226:229], v[12:15]
	v_mfma_f32_16x16x32_bf16 v[4:7], v[160:163], v[226:229], v[4:7]
	v_mfma_f32_16x16x32_bf16 v[60:63], v[148:151], v[188:191], v[60:63]
	v_mfma_f32_16x16x32_bf16 v[52:55], v[164:167], v[188:191], v[52:55]
	v_mfma_f32_16x16x32_bf16 v[44:47], v[148:151], v[214:217], v[44:47]
	v_mfma_f32_16x16x32_bf16 v[36:39], v[164:167], v[214:217], v[36:39]
	v_mfma_f32_16x16x32_bf16 v[28:31], v[148:151], v[222:225], v[28:31]
	v_mfma_f32_16x16x32_bf16 v[20:23], v[164:167], v[222:225], v[20:23]
	v_mfma_f32_16x16x32_bf16 v[12:15], v[148:151], v[230:233], v[12:15]
	v_mfma_f32_16x16x32_bf16 v[4:7], v[164:167], v[230:233], v[4:7]
	v_mfma_f32_16x16x32_bf16 v[56:59], v[168:171], v[184:187], v[56:59]
	v_mfma_f32_16x16x32_bf16 v[48:51], v[176:179], v[184:187], v[48:51]
	v_mfma_f32_16x16x32_bf16 v[40:43], v[168:171], v[204:207], v[40:43]
	v_mfma_f32_16x16x32_bf16 v[32:35], v[176:179], v[204:207], v[32:35]
	v_mfma_f32_16x16x32_bf16 v[24:27], v[168:171], v[218:221], v[24:27]
	v_mfma_f32_16x16x32_bf16 v[16:19], v[176:179], v[218:221], v[16:19]
	v_mfma_f32_16x16x32_bf16 v[8:11], v[168:171], v[226:229], v[8:11]
	v_mfma_f32_16x16x32_bf16 v[0:3], v[176:179], v[226:229], v[0:3]
	v_mfma_f32_16x16x32_bf16 v[56:59], v[172:175], v[188:191], v[56:59]
	v_mfma_f32_16x16x32_bf16 v[48:51], v[180:183], v[188:191], v[48:51]
	v_mfma_f32_16x16x32_bf16 v[40:43], v[172:175], v[214:217], v[40:43]
	v_mfma_f32_16x16x32_bf16 v[32:35], v[180:183], v[214:217], v[32:35]
	v_mfma_f32_16x16x32_bf16 v[24:27], v[172:175], v[222:225], v[24:27]
	v_mfma_f32_16x16x32_bf16 v[16:19], v[180:183], v[222:225], v[16:19]
	v_mfma_f32_16x16x32_bf16 v[8:11], v[172:175], v[230:233], v[8:11]
	v_mfma_f32_16x16x32_bf16 v[0:3], v[180:183], v[230:233], v[0:3]
	s_barrier
	s_add_i32 s60, s60, 2
	s_add_u32 s46, s46, 0x100
	s_addc_u32 s47, s47, 0
	s_add_u32 s56, s56, 0x100
	s_addc_u32 s57, s57, 0
	s_cmp_gt_u32 s60, 13
	s_cbranch_scc0 .LBB0_677
	v_ashrrev_i32_e32 v160, 2, v192
	v_and_b32_e32 v160, 0xffffffc0, v160
	s_lshl_b32 s11, s53, 8
	v_and_or_b32 v142, v192, 15, s11
	v_add_u32_e32 v142, v142, v160
	v_ashrrev_i32_e32 v143, 31, v142
	v_lshl_add_u64 v[144:145], v[142:143], 2, s[90:91]
	global_load_dword v242, v[144:145], off
	global_load_dword v243, v[144:145], off offset:64
	global_load_dword v244, v[144:145], off offset:128
	global_load_dword v245, v[144:145], off offset:192
	global_load_dword v246, v[144:145], off offset:512
	global_load_dword v247, v[144:145], off offset:576
	global_load_dword v248, v[144:145], off offset:640
	global_load_dword v249, v[144:145], off offset:704
	v_readlane_b32 s48, v254, 40
	s_lshl_b32 s46, s52, 7
	v_readlane_b32 s49, v254, 41
	s_ashr_i32 s47, s46, 31
	s_lshl_b64 s[46:47], s[46:47], 1
	s_nop 0
	v_mov_b64_e32 v[162:163], s[48:49]
	v_mad_i64_i32 v[160:161], s[48:49], v142, s28, v[162:163]
	v_lshl_add_u64 v[160:161], v[160:161], 0, s[46:47]
	v_and_b32_e32 v164, 0xc0, v192
	v_mov_b32_e32 v165, v81
	v_lshl_add_u64 v[160:161], v[160:161], 0, v[164:165]
	v_and_b32_e32 v164, 48, v192
	v_lshl_add_u64 v[160:161], v[160:161], 0, v[164:165]
	s_and_b64 vcc, exec, s[6:7]
	s_cbranch_vccz .Lsw1_go
	s_barrier
.Lsw1_go:
	s_waitcnt vmcnt(7)
	v_fmamk_f32 v166, v242, 0x3a800000, v194
	v_mul_f32_e32 v167, 0x4b800000, v166
	v_cmp_gt_f32_e32 vcc, s19, v166
	s_nop 1
	v_cndmask_b32_e32 v166, v166, v167, vcc
	v_rsq_f32_e32 v166, v166
	s_nop 0
	v_mul_f32_e32 v167, 0x45800000, v166
	v_cndmask_b32_e32 v166, v166, v167, vcc
	v_mul_f32_e32 v167, 0xbfb8aa3b, v166
	v_mul_f32_e32 v168, v166, v166
	v_mul_f32_e32 v169, v126, v167
	v_mul_f32_e32 v170, v127, v167
	v_mul_f32_e32 v171, v128, v167
	v_mul_f32_e32 v172, v129, v167
	v_mul_f32_e32 v173, v118, v167
	v_mul_f32_e32 v174, v119, v167
	v_mul_f32_e32 v175, v120, v167
	v_mul_f32_e32 v176, v121, v167
	v_exp_f32_e32 v169, v169
	v_exp_f32_e32 v170, v170
	v_exp_f32_e32 v171, v171
	v_exp_f32_e32 v172, v172
	v_exp_f32_e32 v173, v173
	v_exp_f32_e32 v174, v174
	v_exp_f32_e32 v175, v175
	v_exp_f32_e32 v176, v176
	v_mul_f32_e32 v126, v126, v122
	v_mul_f32_e32 v127, v127, v123
	v_mul_f32_e32 v128, v128, v124
	v_mul_f32_e32 v129, v129, v125
	v_mul_f32_e32 v118, v118, v114
	v_mul_f32_e32 v119, v119, v115
	v_mul_f32_e32 v120, v120, v116
	v_mul_f32_e32 v121, v121, v117
	v_add_f32_e32 v169, 1.0, v169
	v_add_f32_e32 v170, 1.0, v170
	v_add_f32_e32 v171, 1.0, v171
	v_add_f32_e32 v172, 1.0, v172
	v_add_f32_e32 v173, 1.0, v173
	v_add_f32_e32 v174, 1.0, v174
	v_add_f32_e32 v175, 1.0, v175
	v_add_f32_e32 v176, 1.0, v176
	v_rcp_f32_e32 v169, v169
	v_rcp_f32_e32 v170, v170
	v_rcp_f32_e32 v171, v171
	v_rcp_f32_e32 v172, v172
	v_rcp_f32_e32 v173, v173
	v_rcp_f32_e32 v174, v174
	v_rcp_f32_e32 v175, v175
	v_rcp_f32_e32 v176, v176
	v_mul_f32_e32 v126, v126, v168
	v_mul_f32_e32 v127, v127, v168
	v_mul_f32_e32 v128, v128, v168
	v_mul_f32_e32 v129, v129, v168
	v_mul_f32_e32 v118, v118, v168
	v_mul_f32_e32 v119, v119, v168
	v_mul_f32_e32 v120, v120, v168
	v_mul_f32_e32 v121, v121, v168
	v_mul_f32_e32 v126, v126, v169
	v_mul_f32_e32 v127, v127, v170
	v_mul_f32_e32 v128, v128, v171
	v_mul_f32_e32 v129, v129, v172
	v_mul_f32_e32 v118, v118, v173
	v_mul_f32_e32 v119, v119, v174
	v_mul_f32_e32 v120, v120, v175
	v_mul_f32_e32 v121, v121, v176
	v_cvt_pk_bf16_f32 v184, v126, v127
	v_cvt_pk_bf16_f32 v185, v128, v129
	v_cvt_pk_bf16_f32 v186, v118, v119
	v_cvt_pk_bf16_f32 v187, v120, v121
	global_store_dwordx4 v[160:161], v[184:187], off nt
	v_add_co_u32_e32 v160, vcc, 0x16000, v160
	s_nop 1
	v_addc_co_u32_e32 v161, vcc, 0, v161, vcc
	s_waitcnt vmcnt(7)
	v_fmamk_f32 v166, v243, 0x3a800000, v194
	v_mul_f32_e32 v167, 0x4b800000, v166
	v_cmp_gt_f32_e32 vcc, s19, v166
	s_nop 1
	v_cndmask_b32_e32 v166, v166, v167, vcc
	v_rsq_f32_e32 v166, v166
	s_nop 0
	v_mul_f32_e32 v167, 0x45800000, v166
	v_cndmask_b32_e32 v166, v166, v167, vcc
	v_mul_f32_e32 v167, 0xbfb8aa3b, v166
	v_mul_f32_e32 v168, v166, v166
	v_mul_f32_e32 v169, v110, v167
	v_mul_f32_e32 v170, v111, v167
	v_mul_f32_e32 v171, v112, v167
	v_mul_f32_e32 v172, v113, v167
	v_mul_f32_e32 v173, v102, v167
	v_mul_f32_e32 v174, v103, v167
	v_mul_f32_e32 v175, v104, v167
	v_mul_f32_e32 v176, v105, v167
	v_exp_f32_e32 v169, v169
	v_exp_f32_e32 v170, v170
	v_exp_f32_e32 v171, v171
	v_exp_f32_e32 v172, v172
	v_exp_f32_e32 v173, v173
	v_exp_f32_e32 v174, v174
	v_exp_f32_e32 v175, v175
	v_exp_f32_e32 v176, v176
	v_mul_f32_e32 v110, v110, v106
	v_mul_f32_e32 v111, v111, v107
	v_mul_f32_e32 v112, v112, v108
	v_mul_f32_e32 v113, v113, v109
	v_mul_f32_e32 v102, v102, v98
	v_mul_f32_e32 v103, v103, v99
	v_mul_f32_e32 v104, v104, v100
	v_mul_f32_e32 v105, v105, v101
	v_add_f32_e32 v169, 1.0, v169
	v_add_f32_e32 v170, 1.0, v170
	v_add_f32_e32 v171, 1.0, v171
	v_add_f32_e32 v172, 1.0, v172
	v_add_f32_e32 v173, 1.0, v173
	v_add_f32_e32 v174, 1.0, v174
	v_add_f32_e32 v175, 1.0, v175
	v_add_f32_e32 v176, 1.0, v176
	v_rcp_f32_e32 v169, v169
	v_rcp_f32_e32 v170, v170
	v_rcp_f32_e32 v171, v171
	v_rcp_f32_e32 v172, v172
	v_rcp_f32_e32 v173, v173
	v_rcp_f32_e32 v174, v174
	v_rcp_f32_e32 v175, v175
	v_rcp_f32_e32 v176, v176
	v_mul_f32_e32 v110, v110, v168
	v_mul_f32_e32 v111, v111, v168
	v_mul_f32_e32 v112, v112, v168
	v_mul_f32_e32 v113, v113, v168
	v_mul_f32_e32 v102, v102, v168
	v_mul_f32_e32 v103, v103, v168
	v_mul_f32_e32 v104, v104, v168
	v_mul_f32_e32 v105, v105, v168
	v_mul_f32_e32 v110, v110, v169
	v_mul_f32_e32 v111, v111, v170
	v_mul_f32_e32 v112, v112, v171
	v_mul_f32_e32 v113, v113, v172
	v_mul_f32_e32 v102, v102, v173
	v_mul_f32_e32 v103, v103, v174
	v_mul_f32_e32 v104, v104, v175
	v_mul_f32_e32 v105, v105, v176
	v_cvt_pk_bf16_f32 v184, v110, v111
	v_cvt_pk_bf16_f32 v185, v112, v113
	v_cvt_pk_bf16_f32 v186, v102, v103
	v_cvt_pk_bf16_f32 v187, v104, v105
	global_store_dwordx4 v[160:161], v[184:187], off nt
	v_add_co_u32_e32 v160, vcc, 0x16000, v160
	s_nop 1
	v_addc_co_u32_e32 v161, vcc, 0, v161, vcc
	s_waitcnt vmcnt(7)
	v_fmamk_f32 v166, v244, 0x3a800000, v194
	v_mul_f32_e32 v167, 0x4b800000, v166
	v_cmp_gt_f32_e32 vcc, s19, v166
	s_nop 1
	v_cndmask_b32_e32 v166, v166, v167, vcc
	v_rsq_f32_e32 v166, v166
	s_nop 0
	v_mul_f32_e32 v167, 0x45800000, v166
	v_cndmask_b32_e32 v166, v166, v167, vcc
	v_mul_f32_e32 v167, 0xbfb8aa3b, v166
	v_mul_f32_e32 v168, v166, v166
	v_mul_f32_e32 v169, v94, v167
	v_mul_f32_e32 v170, v95, v167
	v_mul_f32_e32 v171, v96, v167
	v_mul_f32_e32 v172, v97, v167
	v_mul_f32_e32 v173, v86, v167
	v_mul_f32_e32 v174, v87, v167
	v_mul_f32_e32 v175, v88, v167
	v_mul_f32_e32 v176, v89, v167
	v_exp_f32_e32 v169, v169
	v_exp_f32_e32 v170, v170
	v_exp_f32_e32 v171, v171
	v_exp_f32_e32 v172, v172
	v_exp_f32_e32 v173, v173
	v_exp_f32_e32 v174, v174
	v_exp_f32_e32 v175, v175
	v_exp_f32_e32 v176, v176
	v_mul_f32_e32 v94, v94, v90
	v_mul_f32_e32 v95, v95, v91
	v_mul_f32_e32 v96, v96, v92
	v_mul_f32_e32 v97, v97, v93
	v_mul_f32_e32 v86, v86, v82
	v_mul_f32_e32 v87, v87, v83
	v_mul_f32_e32 v88, v88, v84
	v_mul_f32_e32 v89, v89, v85
	v_add_f32_e32 v169, 1.0, v169
	v_add_f32_e32 v170, 1.0, v170
	v_add_f32_e32 v171, 1.0, v171
	v_add_f32_e32 v172, 1.0, v172
	v_add_f32_e32 v173, 1.0, v173
	v_add_f32_e32 v174, 1.0, v174
	v_add_f32_e32 v175, 1.0, v175
	v_add_f32_e32 v176, 1.0, v176
	v_rcp_f32_e32 v169, v169
	v_rcp_f32_e32 v170, v170
	v_rcp_f32_e32 v171, v171
	v_rcp_f32_e32 v172, v172
	v_rcp_f32_e32 v173, v173
	v_rcp_f32_e32 v174, v174
	v_rcp_f32_e32 v175, v175
	v_rcp_f32_e32 v176, v176
	v_mul_f32_e32 v94, v94, v168
	v_mul_f32_e32 v95, v95, v168
	v_mul_f32_e32 v96, v96, v168
	v_mul_f32_e32 v97, v97, v168
	v_mul_f32_e32 v86, v86, v168
	v_mul_f32_e32 v87, v87, v168
	v_mul_f32_e32 v88, v88, v168
	v_mul_f32_e32 v89, v89, v168
	v_mul_f32_e32 v94, v94, v169
	v_mul_f32_e32 v95, v95, v170
	v_mul_f32_e32 v96, v96, v171
	v_mul_f32_e32 v97, v97, v172
	v_mul_f32_e32 v86, v86, v173
	v_mul_f32_e32 v87, v87, v174
	v_mul_f32_e32 v88, v88, v175
	v_mul_f32_e32 v89, v89, v176
	v_cvt_pk_bf16_f32 v184, v94, v95
	v_cvt_pk_bf16_f32 v185, v96, v97
	v_cvt_pk_bf16_f32 v186, v86, v87
	v_cvt_pk_bf16_f32 v187, v88, v89
	global_store_dwordx4 v[160:161], v[184:187], off nt
	v_add_co_u32_e32 v160, vcc, 0x16000, v160
	s_nop 1
	v_addc_co_u32_e32 v161, vcc, 0, v161, vcc
	s_waitcnt vmcnt(7)
	v_fmamk_f32 v166, v245, 0x3a800000, v194
	v_mul_f32_e32 v167, 0x4b800000, v166
	v_cmp_gt_f32_e32 vcc, s19, v166
	s_nop 1
	v_cndmask_b32_e32 v166, v166, v167, vcc
	v_rsq_f32_e32 v166, v166
	s_nop 0
	v_mul_f32_e32 v167, 0x45800000, v166
	v_cndmask_b32_e32 v166, v166, v167, vcc
	v_mul_f32_e32 v167, 0xbfb8aa3b, v166
	v_mul_f32_e32 v168, v166, v166
	v_mul_f32_e32 v169, v76, v167
	v_mul_f32_e32 v170, v77, v167
	v_mul_f32_e32 v171, v78, v167
	v_mul_f32_e32 v172, v79, v167
	v_mul_f32_e32 v173, v68, v167
	v_mul_f32_e32 v174, v69, v167
	v_mul_f32_e32 v175, v70, v167
	v_mul_f32_e32 v176, v71, v167
	v_exp_f32_e32 v169, v169
	v_exp_f32_e32 v170, v170
	v_exp_f32_e32 v171, v171
	v_exp_f32_e32 v172, v172
	v_exp_f32_e32 v173, v173
	v_exp_f32_e32 v174, v174
	v_exp_f32_e32 v175, v175
	v_exp_f32_e32 v176, v176
	v_mul_f32_e32 v76, v76, v72
	v_mul_f32_e32 v77, v77, v73
	v_mul_f32_e32 v78, v78, v74
	v_mul_f32_e32 v79, v79, v75
	v_mul_f32_e32 v68, v68, v64
	v_mul_f32_e32 v69, v69, v65
	v_mul_f32_e32 v70, v70, v66
	v_mul_f32_e32 v71, v71, v67
	v_add_f32_e32 v169, 1.0, v169
	v_add_f32_e32 v170, 1.0, v170
	v_add_f32_e32 v171, 1.0, v171
	v_add_f32_e32 v172, 1.0, v172
	v_add_f32_e32 v173, 1.0, v173
	v_add_f32_e32 v174, 1.0, v174
	v_add_f32_e32 v175, 1.0, v175
	v_add_f32_e32 v176, 1.0, v176
	v_rcp_f32_e32 v169, v169
	v_rcp_f32_e32 v170, v170
	v_rcp_f32_e32 v171, v171
	v_rcp_f32_e32 v172, v172
	v_rcp_f32_e32 v173, v173
	v_rcp_f32_e32 v174, v174
	v_rcp_f32_e32 v175, v175
	v_rcp_f32_e32 v176, v176
	v_mul_f32_e32 v76, v76, v168
	v_mul_f32_e32 v77, v77, v168
	v_mul_f32_e32 v78, v78, v168
	v_mul_f32_e32 v79, v79, v168
	v_mul_f32_e32 v68, v68, v168
	v_mul_f32_e32 v69, v69, v168
	v_mul_f32_e32 v70, v70, v168
	v_mul_f32_e32 v71, v71, v168
	v_mul_f32_e32 v76, v76, v169
	v_mul_f32_e32 v77, v77, v170
	v_mul_f32_e32 v78, v78, v171
	v_mul_f32_e32 v79, v79, v172
	v_mul_f32_e32 v68, v68, v173
	v_mul_f32_e32 v69, v69, v174
	v_mul_f32_e32 v70, v70, v175
	v_mul_f32_e32 v71, v71, v176
	v_cvt_pk_bf16_f32 v184, v76, v77
	v_cvt_pk_bf16_f32 v185, v78, v79
	v_cvt_pk_bf16_f32 v186, v68, v69
	v_cvt_pk_bf16_f32 v187, v70, v71
	global_store_dwordx4 v[160:161], v[184:187], off nt
	v_add_co_u32_e32 v160, vcc, 0x6e000, v160
	s_nop 1
	v_addc_co_u32_e32 v161, vcc, 0, v161, vcc
	s_waitcnt vmcnt(7)
	v_fmamk_f32 v166, v246, 0x3a800000, v194
	v_mul_f32_e32 v167, 0x4b800000, v166
	v_cmp_gt_f32_e32 vcc, s19, v166
	s_nop 1
	v_cndmask_b32_e32 v166, v166, v167, vcc
	v_rsq_f32_e32 v166, v166
	s_nop 0
	v_mul_f32_e32 v167, 0x45800000, v166
	v_cndmask_b32_e32 v166, v166, v167, vcc
	v_mul_f32_e32 v167, 0xbfb8aa3b, v166
	v_mul_f32_e32 v168, v166, v166
	v_mul_f32_e32 v169, v60, v167
	v_mul_f32_e32 v170, v61, v167
	v_mul_f32_e32 v171, v62, v167
	v_mul_f32_e32 v172, v63, v167
	v_mul_f32_e32 v173, v52, v167
	v_mul_f32_e32 v174, v53, v167
	v_mul_f32_e32 v175, v54, v167
	v_mul_f32_e32 v176, v55, v167
	v_exp_f32_e32 v169, v169
	v_exp_f32_e32 v170, v170
	v_exp_f32_e32 v171, v171
	v_exp_f32_e32 v172, v172
	v_exp_f32_e32 v173, v173
	v_exp_f32_e32 v174, v174
	v_exp_f32_e32 v175, v175
	v_exp_f32_e32 v176, v176
	v_mul_f32_e32 v60, v60, v56
	v_mul_f32_e32 v61, v61, v57
	v_mul_f32_e32 v62, v62, v58
	v_mul_f32_e32 v63, v63, v59
	v_mul_f32_e32 v52, v52, v48
	v_mul_f32_e32 v53, v53, v49
	v_mul_f32_e32 v54, v54, v50
	v_mul_f32_e32 v55, v55, v51
	v_add_f32_e32 v169, 1.0, v169
	v_add_f32_e32 v170, 1.0, v170
	v_add_f32_e32 v171, 1.0, v171
	v_add_f32_e32 v172, 1.0, v172
	v_add_f32_e32 v173, 1.0, v173
	v_add_f32_e32 v174, 1.0, v174
	v_add_f32_e32 v175, 1.0, v175
	v_add_f32_e32 v176, 1.0, v176
	v_rcp_f32_e32 v169, v169
	v_rcp_f32_e32 v170, v170
	v_rcp_f32_e32 v171, v171
	v_rcp_f32_e32 v172, v172
	v_rcp_f32_e32 v173, v173
	v_rcp_f32_e32 v174, v174
	v_rcp_f32_e32 v175, v175
	v_rcp_f32_e32 v176, v176
	v_mul_f32_e32 v60, v60, v168
	v_mul_f32_e32 v61, v61, v168
	v_mul_f32_e32 v62, v62, v168
	v_mul_f32_e32 v63, v63, v168
	v_mul_f32_e32 v52, v52, v168
	v_mul_f32_e32 v53, v53, v168
	v_mul_f32_e32 v54, v54, v168
	v_mul_f32_e32 v55, v55, v168
	v_mul_f32_e32 v60, v60, v169
	v_mul_f32_e32 v61, v61, v170
	v_mul_f32_e32 v62, v62, v171
	v_mul_f32_e32 v63, v63, v172
	v_mul_f32_e32 v52, v52, v173
	v_mul_f32_e32 v53, v53, v174
	v_mul_f32_e32 v54, v54, v175
	v_mul_f32_e32 v55, v55, v176
	v_cvt_pk_bf16_f32 v184, v60, v61
	v_cvt_pk_bf16_f32 v185, v62, v63
	v_cvt_pk_bf16_f32 v186, v52, v53
	v_cvt_pk_bf16_f32 v187, v54, v55
	global_store_dwordx4 v[160:161], v[184:187], off nt
	v_add_co_u32_e32 v160, vcc, 0x16000, v160
	s_nop 1
	v_addc_co_u32_e32 v161, vcc, 0, v161, vcc
	s_waitcnt vmcnt(7)
	v_fmamk_f32 v166, v247, 0x3a800000, v194
	v_mul_f32_e32 v167, 0x4b800000, v166
	v_cmp_gt_f32_e32 vcc, s19, v166
	s_nop 1
	v_cndmask_b32_e32 v166, v166, v167, vcc
	v_rsq_f32_e32 v166, v166
	s_nop 0
	v_mul_f32_e32 v167, 0x45800000, v166
	v_cndmask_b32_e32 v166, v166, v167, vcc
	v_mul_f32_e32 v167, 0xbfb8aa3b, v166
	v_mul_f32_e32 v168, v166, v166
	v_mul_f32_e32 v169, v44, v167
	v_mul_f32_e32 v170, v45, v167
	v_mul_f32_e32 v171, v46, v167
	v_mul_f32_e32 v172, v47, v167
	v_mul_f32_e32 v173, v36, v167
	v_mul_f32_e32 v174, v37, v167
	v_mul_f32_e32 v175, v38, v167
	v_mul_f32_e32 v176, v39, v167
	v_exp_f32_e32 v169, v169
	v_exp_f32_e32 v170, v170
	v_exp_f32_e32 v171, v171
	v_exp_f32_e32 v172, v172
	v_exp_f32_e32 v173, v173
	v_exp_f32_e32 v174, v174
	v_exp_f32_e32 v175, v175
	v_exp_f32_e32 v176, v176
	v_mul_f32_e32 v44, v44, v40
	v_mul_f32_e32 v45, v45, v41
	v_mul_f32_e32 v46, v46, v42
	v_mul_f32_e32 v47, v47, v43
	v_mul_f32_e32 v36, v36, v32
	v_mul_f32_e32 v37, v37, v33
	v_mul_f32_e32 v38, v38, v34
	v_mul_f32_e32 v39, v39, v35
	v_add_f32_e32 v169, 1.0, v169
	v_add_f32_e32 v170, 1.0, v170
	v_add_f32_e32 v171, 1.0, v171
	v_add_f32_e32 v172, 1.0, v172
	v_add_f32_e32 v173, 1.0, v173
	v_add_f32_e32 v174, 1.0, v174
	v_add_f32_e32 v175, 1.0, v175
	v_add_f32_e32 v176, 1.0, v176
	v_rcp_f32_e32 v169, v169
	v_rcp_f32_e32 v170, v170
	v_rcp_f32_e32 v171, v171
	v_rcp_f32_e32 v172, v172
	v_rcp_f32_e32 v173, v173
	v_rcp_f32_e32 v174, v174
	v_rcp_f32_e32 v175, v175
	v_rcp_f32_e32 v176, v176
	v_mul_f32_e32 v44, v44, v168
	v_mul_f32_e32 v45, v45, v168
	v_mul_f32_e32 v46, v46, v168
	v_mul_f32_e32 v47, v47, v168
	v_mul_f32_e32 v36, v36, v168
	v_mul_f32_e32 v37, v37, v168
	v_mul_f32_e32 v38, v38, v168
	v_mul_f32_e32 v39, v39, v168
	v_mul_f32_e32 v44, v44, v169
	v_mul_f32_e32 v45, v45, v170
	v_mul_f32_e32 v46, v46, v171
	v_mul_f32_e32 v47, v47, v172
	v_mul_f32_e32 v36, v36, v173
	v_mul_f32_e32 v37, v37, v174
	v_mul_f32_e32 v38, v38, v175
	v_mul_f32_e32 v39, v39, v176
	v_cvt_pk_bf16_f32 v184, v44, v45
	v_cvt_pk_bf16_f32 v185, v46, v47
	v_cvt_pk_bf16_f32 v186, v36, v37
	v_cvt_pk_bf16_f32 v187, v38, v39
	global_store_dwordx4 v[160:161], v[184:187], off nt
	v_add_co_u32_e32 v160, vcc, 0x16000, v160
	s_nop 1
	v_addc_co_u32_e32 v161, vcc, 0, v161, vcc
	s_waitcnt vmcnt(7)
	v_fmamk_f32 v166, v248, 0x3a800000, v194
	v_mul_f32_e32 v167, 0x4b800000, v166
	v_cmp_gt_f32_e32 vcc, s19, v166
	s_nop 1
	v_cndmask_b32_e32 v166, v166, v167, vcc
	v_rsq_f32_e32 v166, v166
	s_nop 0
	v_mul_f32_e32 v167, 0x45800000, v166
	v_cndmask_b32_e32 v166, v166, v167, vcc
	v_mul_f32_e32 v167, 0xbfb8aa3b, v166
	v_mul_f32_e32 v168, v166, v166
	v_mul_f32_e32 v169, v28, v167
	v_mul_f32_e32 v170, v29, v167
	v_mul_f32_e32 v171, v30, v167
	v_mul_f32_e32 v172, v31, v167
	v_mul_f32_e32 v173, v20, v167
	v_mul_f32_e32 v174, v21, v167
	v_mul_f32_e32 v175, v22, v167
	v_mul_f32_e32 v176, v23, v167
	v_exp_f32_e32 v169, v169
	v_exp_f32_e32 v170, v170
	v_exp_f32_e32 v171, v171
	v_exp_f32_e32 v172, v172
	v_exp_f32_e32 v173, v173
	v_exp_f32_e32 v174, v174
	v_exp_f32_e32 v175, v175
	v_exp_f32_e32 v176, v176
	v_mul_f32_e32 v28, v28, v24
	v_mul_f32_e32 v29, v29, v25
	v_mul_f32_e32 v30, v30, v26
	v_mul_f32_e32 v31, v31, v27
	v_mul_f32_e32 v20, v20, v16
	v_mul_f32_e32 v21, v21, v17
	v_mul_f32_e32 v22, v22, v18
	v_mul_f32_e32 v23, v23, v19
	v_add_f32_e32 v169, 1.0, v169
	v_add_f32_e32 v170, 1.0, v170
	v_add_f32_e32 v171, 1.0, v171
	v_add_f32_e32 v172, 1.0, v172
	v_add_f32_e32 v173, 1.0, v173
	v_add_f32_e32 v174, 1.0, v174
	v_add_f32_e32 v175, 1.0, v175
	v_add_f32_e32 v176, 1.0, v176
	v_rcp_f32_e32 v169, v169
	v_rcp_f32_e32 v170, v170
	v_rcp_f32_e32 v171, v171
	v_rcp_f32_e32 v172, v172
	v_rcp_f32_e32 v173, v173
	v_rcp_f32_e32 v174, v174
	v_rcp_f32_e32 v175, v175
	v_rcp_f32_e32 v176, v176
	v_mul_f32_e32 v28, v28, v168
	v_mul_f32_e32 v29, v29, v168
	v_mul_f32_e32 v30, v30, v168
	v_mul_f32_e32 v31, v31, v168
	v_mul_f32_e32 v20, v20, v168
	v_mul_f32_e32 v21, v21, v168
	v_mul_f32_e32 v22, v22, v168
	v_mul_f32_e32 v23, v23, v168
	v_mul_f32_e32 v28, v28, v169
	v_mul_f32_e32 v29, v29, v170
	v_mul_f32_e32 v30, v30, v171
	v_mul_f32_e32 v31, v31, v172
	v_mul_f32_e32 v20, v20, v173
	v_mul_f32_e32 v21, v21, v174
	v_mul_f32_e32 v22, v22, v175
	v_mul_f32_e32 v23, v23, v176
	v_cvt_pk_bf16_f32 v184, v28, v29
	v_cvt_pk_bf16_f32 v185, v30, v31
	v_cvt_pk_bf16_f32 v186, v20, v21
	v_cvt_pk_bf16_f32 v187, v22, v23
	global_store_dwordx4 v[160:161], v[184:187], off nt
	v_add_co_u32_e32 v160, vcc, 0x16000, v160
	s_nop 1
	v_addc_co_u32_e32 v161, vcc, 0, v161, vcc
	s_waitcnt vmcnt(7)
	v_fmamk_f32 v166, v249, 0x3a800000, v194
	v_mul_f32_e32 v167, 0x4b800000, v166
	v_cmp_gt_f32_e32 vcc, s19, v166
	s_nop 1
	v_cndmask_b32_e32 v166, v166, v167, vcc
	v_rsq_f32_e32 v166, v166
	s_nop 0
	v_mul_f32_e32 v167, 0x45800000, v166
	v_cndmask_b32_e32 v166, v166, v167, vcc
	v_mul_f32_e32 v167, 0xbfb8aa3b, v166
	v_mul_f32_e32 v168, v166, v166
	v_mul_f32_e32 v169, v12, v167
	v_mul_f32_e32 v170, v13, v167
	v_mul_f32_e32 v171, v14, v167
	v_mul_f32_e32 v172, v15, v167
	v_mul_f32_e32 v173, v4, v167
	v_mul_f32_e32 v174, v5, v167
	v_mul_f32_e32 v175, v6, v167
	v_mul_f32_e32 v176, v7, v167
	v_exp_f32_e32 v169, v169
	v_exp_f32_e32 v170, v170
	v_exp_f32_e32 v171, v171
	v_exp_f32_e32 v172, v172
	v_exp_f32_e32 v173, v173
	v_exp_f32_e32 v174, v174
	v_exp_f32_e32 v175, v175
	v_exp_f32_e32 v176, v176
	v_mul_f32_e32 v12, v12, v8
	v_mul_f32_e32 v13, v13, v9
	v_mul_f32_e32 v14, v14, v10
	v_mul_f32_e32 v15, v15, v11
	v_mul_f32_e32 v4, v4, v0
	v_mul_f32_e32 v5, v5, v1
	v_mul_f32_e32 v6, v6, v2
	v_mul_f32_e32 v7, v7, v3
	v_add_f32_e32 v169, 1.0, v169
	v_add_f32_e32 v170, 1.0, v170
	v_add_f32_e32 v171, 1.0, v171
	v_add_f32_e32 v172, 1.0, v172
	v_add_f32_e32 v173, 1.0, v173
	v_add_f32_e32 v174, 1.0, v174
	v_add_f32_e32 v175, 1.0, v175
	v_add_f32_e32 v176, 1.0, v176
	v_rcp_f32_e32 v169, v169
	v_rcp_f32_e32 v170, v170
	v_rcp_f32_e32 v171, v171
	v_rcp_f32_e32 v172, v172
	v_rcp_f32_e32 v173, v173
	v_rcp_f32_e32 v174, v174
	v_rcp_f32_e32 v175, v175
	v_rcp_f32_e32 v176, v176
	v_mul_f32_e32 v12, v12, v168
	v_mul_f32_e32 v13, v13, v168
	v_mul_f32_e32 v14, v14, v168
	v_mul_f32_e32 v15, v15, v168
	v_mul_f32_e32 v4, v4, v168
	v_mul_f32_e32 v5, v5, v168
	v_mul_f32_e32 v6, v6, v168
	v_mul_f32_e32 v7, v7, v168
	v_mul_f32_e32 v12, v12, v169
	v_mul_f32_e32 v13, v13, v170
	v_mul_f32_e32 v14, v14, v171
	v_mul_f32_e32 v15, v15, v172
	v_mul_f32_e32 v4, v4, v173
	v_mul_f32_e32 v5, v5, v174
	v_mul_f32_e32 v6, v6, v175
	v_mul_f32_e32 v7, v7, v176
	v_cvt_pk_bf16_f32 v184, v12, v13
	v_cvt_pk_bf16_f32 v185, v14, v15
	v_cvt_pk_bf16_f32 v186, v4, v5
	v_cvt_pk_bf16_f32 v187, v6, v7
	global_store_dwordx4 v[160:161], v[184:187], off nt
	s_andn2_b64 vcc, exec, s[40:41]
	s_mov_b64 s[46:47], -1
	s_cbranch_vccnz .LBB0_673
	s_andn2_b64 vcc, exec, s[0:1]
	s_cbranch_vccnz .LBB0_672
	s_barrier
	s_branch .LBB0_672
